# GEMM K-loops: hoisted SP2 address blocks and loop-tail counter adds moved into MFMA segments, m0 for first SP2 DMA preset before the barrier, s_setprio removed from the loops
# speedup vs baseline: 1.0046x; 1.0046x over previous
; #define PG8_STAGE(bufoff, gbase, voff) do { _Pragma("unroll") for (int _i = 0; _i < 2; ++_i) \
;         __builtin_amdgcn_global_load_lds((const unsigned*)((const char*)(gbase) + (voff)[_i]), (PG8_LAS unsigned*)(lds + (bufoff) + ldsw + _i * 8192), 16, 0, 0); } while (0)
; #define PG8_LDA(dst, b, h) do { _Pragma("unroll") for (int m = 0; m < 4; ++m) _Pragma("unroll") for (int k = 0; k < 2; ++k) dst[m][k] = *(const PG8_LAS bf16x8*)(lds + PG8_SA(b, h) + aoff + m * 2048 + k * 1024); } while (0)
; #define PG8_LDB(dst, b, h) do { _Pragma("unroll") for (int n = 0; n < 2; ++n) _Pragma("unroll") for (int k = 0; k < 2; ++k) dst[n][k] = *(const PG8_LAS bf16x8*)(lds + PG8_SB(b, h) + boff + n * 2048 + k * 1024); } while (0)
; #define PG8_MMA(ai, bj, At, Bt) do { __builtin_amdgcn_s_setprio(1); _Pragma("unroll") for (int m = 0; m < 4; ++m) _Pragma("unroll") for (int n = 0; n < 2; ++n) _Pragma("unroll") for (int k = 0; k < 2; ++k) \
;         acc[ai][bj][m][n] = __builtin_amdgcn_mfma_f32_16x16x32_bf16(Bt[n][k], At[m][k], acc[ai][bj][m][n], 0, 0, 0); __builtin_amdgcn_s_setprio(0); } while (0)
; #define PG8_WAIT_V(n) asm volatile("s_waitcnt vmcnt(" #n ")" ::: "memory")
; #define PG8_WAIT_L(n) asm volatile("s_waitcnt lgkmcnt(" #n ")" ::: "memory")
; template <class Epi, class Sched, bool ALIGN_EPI = false, bool SP2 = false>
; __device__ __forceinline__ void gemm_phase(PG8_LAS unsigned char* lds, const Gemm g, const Sched& S, const Epi& E) {
;     ...
;             const bool last = (t == nt - 2);
;             const char* a1 = cA + (size_t)(t + 1) * kstep;
;             const char* a2 = last ? nA : cA + (size_t)(t + 2) * kstep; const char* b2 = last ? nB : cB + (size_t)(t + 2) * kstep;
;             const char* a3 = a2 + kstep; const char* b3 = b2 + kstep;
;             if (last && has_next) S.a_ready(nxt);
;             if constexpr (SP2) {
;             PG8_LDB(B0, 0, 0); PG8_LDB(B1, 0, 1); PG8_SCHED; PG8_LDA(At, 0, 0); PG8_STAGE(PG8_SA(1, 1), a1 + hstep, voffA);
;             PG8_WAIT_V(8); PG8_WAIT_L(0); PG8_BAR; PG8_MMA(0, 0, At, B0); PG8_MMA(0, 1, At, B1); PG8_BAR; PG8_SCHED;
;             PG8_LDA(At, 0, 1); PG8_STAGE(PG8_SB(0, 0), b2, voffB); PG8_STAGE(PG8_SB(0, 1), b2 + hstep, voffB); PG8_STAGE(PG8_SA(0, 0), a2, voffA);
;             PG8_WAIT_V(8); PG8_WAIT_L(0); PG8_BAR; PG8_MMA(1, 0, At, B0); PG8_MMA(1, 1, At, B1); PG8_BAR; PG8_SCHED;
.LBB0_150:
	ds_read_b128 v[144:147], v155
	ds_read_b128 v[148:151], v155 offset:1024
	ds_read_b128 v[160:163], v155 offset:2048
	ds_read_b128 v[164:167], v155 offset:3072
	ds_read_b128 v[168:171], v156
	ds_read_b128 v[172:175], v156 offset:1024
	ds_read_b128 v[176:179], v156 offset:2048
	ds_read_b128 v[180:183], v156 offset:3072
	s_add_u32 s30, s28, 0xfff80080
	s_addc_u32 s31, s29, -1
	s_cmp_eq_u32 s60, 28
	s_cselect_b32 s35, s15, s31
	s_cselect_b32 s34, s56, s30
	s_cselect_b32 s31, s13, s59
	s_cselect_b32 s30, s57, s58
	v_lshl_add_u64 v[216:217], s[28:29], 0, v[136:137]
	s_add_i32 m0, s25, 0xc000
	ds_read_b128 v[184:187], v157
	ds_read_b128 v[188:191], v157 offset:1024
	ds_read_b128 v[192:195], v157 offset:2048
	ds_read_b128 v[196:199], v157 offset:3072
	ds_read_b128 v[200:203], v157 offset:4096
	ds_read_b128 v[204:207], v157 offset:5120
	ds_read_b128 v[208:211], v157 offset:6144
	ds_read_b128 v[212:215], v157 offset:7168
	global_load_lds_dwordx4 v[216:217], off
	v_lshl_add_u64 v[216:217], s[28:29], 0, v[138:139]
	s_add_i32 m0, s25, 0xe000
	s_nop 0
	global_load_lds_dwordx4 v[216:217], off
	s_mov_b32 m0, s48
	s_nop 0
	global_load_lds_dwordx4 v[250:251], off
	s_mov_b32 m0, s49
	s_nop 0
	global_load_lds_dwordx4 v[252:253], off
	s_waitcnt vmcnt(10)
	s_waitcnt lgkmcnt(0)
	s_barrier
	s_waitcnt lgkmcnt(0)
	v_mfma_f32_16x16x32_bf16 v[124:127], v[144:147], v[184:187], v[124:127]
	v_mfma_f32_16x16x32_bf16 v[120:123], v[160:163], v[184:187], v[120:123]
	s_add_u32 s62, s30, 0x80000
	v_mfma_f32_16x16x32_bf16 v[108:111], v[144:147], v[192:195], v[108:111]
	v_mfma_f32_16x16x32_bf16 v[104:107], v[160:163], v[192:195], v[104:107]
	s_addc_u32 s63, s31, 0
	v_mfma_f32_16x16x32_bf16 v[92:95], v[144:147], v[200:203], v[92:95]
	v_mfma_f32_16x16x32_bf16 v[88:91], v[160:163], v[200:203], v[88:91]
	v_lshl_add_u64 v[216:217], s[30:31], 0, v[132:133]
	v_mfma_f32_16x16x32_bf16 v[76:79], v[144:147], v[208:211], v[76:79]
	v_mfma_f32_16x16x32_bf16 v[72:75], v[160:163], v[208:211], v[72:75]
	v_lshl_add_u64 v[218:219], s[30:31], 0, v[128:129]
	v_mfma_f32_16x16x32_bf16 v[124:127], v[148:151], v[188:191], v[124:127]
	v_mfma_f32_16x16x32_bf16 v[120:123], v[164:167], v[188:191], v[120:123]
	v_lshl_add_u64 v[246:247], s[62:63], 0, v[132:133]
	v_mfma_f32_16x16x32_bf16 v[108:111], v[148:151], v[196:199], v[108:111]
	v_mfma_f32_16x16x32_bf16 v[104:107], v[164:167], v[196:199], v[104:107]
	v_lshl_add_u64 v[222:223], s[34:35], 0, v[130:131]
	v_mfma_f32_16x16x32_bf16 v[92:95], v[148:151], v[204:207], v[92:95]
	v_mfma_f32_16x16x32_bf16 v[88:91], v[164:167], v[204:207], v[88:91]
	v_lshl_add_u64 v[248:249], s[62:63], 0, v[128:129]
	v_mfma_f32_16x16x32_bf16 v[76:79], v[148:151], v[212:215], v[76:79]
	v_mfma_f32_16x16x32_bf16 v[72:75], v[164:167], v[212:215], v[72:75]
	v_lshl_add_u64 v[220:221], s[34:35], 0, v[134:135]
	v_mfma_f32_16x16x32_bf16 v[116:119], v[168:171], v[184:187], v[116:119]
	v_mfma_f32_16x16x32_bf16 v[112:115], v[176:179], v[184:187], v[112:115]
	v_mfma_f32_16x16x32_bf16 v[100:103], v[168:171], v[192:195], v[100:103]
	v_mfma_f32_16x16x32_bf16 v[96:99], v[176:179], v[192:195], v[96:99]
	v_mfma_f32_16x16x32_bf16 v[84:87], v[168:171], v[200:203], v[84:87]
	v_mfma_f32_16x16x32_bf16 v[80:83], v[176:179], v[200:203], v[80:83]
	v_mfma_f32_16x16x32_bf16 v[68:71], v[168:171], v[208:211], v[68:71]
	v_mfma_f32_16x16x32_bf16 v[64:67], v[176:179], v[208:211], v[64:67]
	v_mfma_f32_16x16x32_bf16 v[116:119], v[172:175], v[188:191], v[116:119]
	v_mfma_f32_16x16x32_bf16 v[112:115], v[180:183], v[188:191], v[112:115]
	v_mfma_f32_16x16x32_bf16 v[100:103], v[172:175], v[196:199], v[100:103]
	v_mfma_f32_16x16x32_bf16 v[96:99], v[180:183], v[196:199], v[96:99]
	v_mfma_f32_16x16x32_bf16 v[84:87], v[172:175], v[204:207], v[84:87]
	v_mfma_f32_16x16x32_bf16 v[80:83], v[180:183], v[204:207], v[80:83]
	v_mfma_f32_16x16x32_bf16 v[68:71], v[172:175], v[212:215], v[68:71]
	v_mfma_f32_16x16x32_bf16 v[64:67], v[180:183], v[212:215], v[64:67]
	s_add_i32 s61, s52, s42
	s_mov_b32 m0, s61
	s_barrier
	global_load_lds_dwordx4 v[216:217], off
	s_add_i32 m0, s61, 0x2000
	s_add_i32 s61, s53, s42
	global_load_lds_dwordx4 v[218:219], off
	s_mov_b32 m0, s61
	s_nop 0
	global_load_lds_dwordx4 v[246:247], off
	s_add_i32 m0, s61, 0x2000
	s_nop 0
	global_load_lds_dwordx4 v[248:249], off
	ds_read_b128 v[184:187], v157 offset:16384
	ds_read_b128 v[188:191], v157 offset:17408
	ds_read_b128 v[192:195], v157 offset:18432
	ds_read_b128 v[196:199], v157 offset:19456
	ds_read_b128 v[200:203], v157 offset:20480
	ds_read_b128 v[204:207], v157 offset:21504
	ds_read_b128 v[208:211], v157 offset:22528
	ds_read_b128 v[212:215], v157 offset:23552
	s_waitcnt vmcnt(4)
	s_waitcnt lgkmcnt(0)
	s_barrier
; #define PG8_STAGE(bufoff, gbase, voff) do { _Pragma("unroll") for (int _i = 0; _i < 2; ++_i) \
;         __builtin_amdgcn_global_load_lds((const unsigned*)((const char*)(gbase) + (voff)[_i]), (PG8_LAS unsigned*)(lds + (bufoff) + ldsw + _i * 8192), 16, 0, 0); } while (0)
; #define PG8_LDA(dst, b, h) do { _Pragma("unroll") for (int m = 0; m < 4; ++m) _Pragma("unroll") for (int k = 0; k < 2; ++k) dst[m][k] = *(const PG8_LAS bf16x8*)(lds + PG8_SA(b, h) + aoff + m * 2048 + k * 1024); } while (0)
; #define PG8_LDB(dst, b, h) do { _Pragma("unroll") for (int n = 0; n < 2; ++n) _Pragma("unroll") for (int k = 0; k < 2; ++k) dst[n][k] = *(const PG8_LAS bf16x8*)(lds + PG8_SB(b, h) + boff + n * 2048 + k * 1024); } while (0)
; #define PG8_MMA(ai, bj, At, Bt) do { __builtin_amdgcn_s_setprio(1); _Pragma("unroll") for (int m = 0; m < 4; ++m) _Pragma("unroll") for (int n = 0; n < 2; ++n) _Pragma("unroll") for (int k = 0; k < 2; ++k) \
;         acc[ai][bj][m][n] = __builtin_amdgcn_mfma_f32_16x16x32_bf16(Bt[n][k], At[m][k], acc[ai][bj][m][n], 0, 0, 0); __builtin_amdgcn_s_setprio(0); } while (0)
; #define PG8_WAIT_V(n) asm volatile("s_waitcnt vmcnt(" #n ")" ::: "memory")
; #define PG8_WAIT_L(n) asm volatile("s_waitcnt lgkmcnt(" #n ")" ::: "memory")
; #define PG8_BAR __builtin_amdgcn_s_barrier()
; #define PG8_SCHED __builtin_amdgcn_sched_barrier(0)
; template <class Epi, class Sched, bool ALIGN_EPI = false, bool SP2 = false>
; __device__ __forceinline__ void gemm_phase(PG8_LAS unsigned char* lds, const Gemm g, const Sched& S, const Epi& E) {
;     ...
;             PG8_WAIT_V(8); PG8_WAIT_L(0); PG8_BAR; PG8_MMA(1, 0, At, B0); PG8_MMA(1, 1, At, B1); PG8_BAR; PG8_SCHED;
;             PG8_LDB(B0, 1, 0); PG8_LDB(B1, 1, 1); PG8_SCHED; PG8_LDA(At, 1, 0); PG8_STAGE(PG8_SA(0, 1), a2 + hstep, voffA);
;             PG8_WAIT_V(8); PG8_WAIT_L(0); PG8_BAR; PG8_MMA(0, 0, At, B0); PG8_MMA(0, 1, At, B1); PG8_BAR; PG8_SCHED;
	s_waitcnt lgkmcnt(0)
	v_mfma_f32_16x16x32_bf16 v[60:63], v[144:147], v[184:187], v[60:63]
	v_mfma_f32_16x16x32_bf16 v[56:59], v[160:163], v[184:187], v[56:59]
	v_mfma_f32_16x16x32_bf16 v[44:47], v[144:147], v[192:195], v[44:47]
	v_mfma_f32_16x16x32_bf16 v[40:43], v[160:163], v[192:195], v[40:43]
	v_mfma_f32_16x16x32_bf16 v[28:31], v[144:147], v[200:203], v[28:31]
	v_mfma_f32_16x16x32_bf16 v[24:27], v[160:163], v[200:203], v[24:27]
	v_mfma_f32_16x16x32_bf16 v[12:15], v[144:147], v[208:211], v[12:15]
	v_mfma_f32_16x16x32_bf16 v[8:11], v[160:163], v[208:211], v[8:11]
	v_mfma_f32_16x16x32_bf16 v[60:63], v[148:151], v[188:191], v[60:63]
	v_mfma_f32_16x16x32_bf16 v[56:59], v[164:167], v[188:191], v[56:59]
	v_mfma_f32_16x16x32_bf16 v[44:47], v[148:151], v[196:199], v[44:47]
	v_mfma_f32_16x16x32_bf16 v[40:43], v[164:167], v[196:199], v[40:43]
	v_mfma_f32_16x16x32_bf16 v[28:31], v[148:151], v[204:207], v[28:31]
	v_mfma_f32_16x16x32_bf16 v[24:27], v[164:167], v[204:207], v[24:27]
	v_mfma_f32_16x16x32_bf16 v[12:15], v[148:151], v[212:215], v[12:15]
	v_mfma_f32_16x16x32_bf16 v[8:11], v[164:167], v[212:215], v[8:11]
	v_mfma_f32_16x16x32_bf16 v[52:55], v[168:171], v[184:187], v[52:55]
	v_mfma_f32_16x16x32_bf16 v[48:51], v[176:179], v[184:187], v[48:51]
	v_mfma_f32_16x16x32_bf16 v[36:39], v[168:171], v[192:195], v[36:39]
	v_mfma_f32_16x16x32_bf16 v[32:35], v[176:179], v[192:195], v[32:35]
	v_mfma_f32_16x16x32_bf16 v[20:23], v[168:171], v[200:203], v[20:23]
	v_mfma_f32_16x16x32_bf16 v[16:19], v[176:179], v[200:203], v[16:19]
	v_mfma_f32_16x16x32_bf16 v[4:7], v[168:171], v[208:211], v[4:7]
	v_mfma_f32_16x16x32_bf16 v[0:3], v[176:179], v[208:211], v[0:3]
	v_mfma_f32_16x16x32_bf16 v[52:55], v[172:175], v[188:191], v[52:55]
	v_mfma_f32_16x16x32_bf16 v[48:51], v[180:183], v[188:191], v[48:51]
	v_mfma_f32_16x16x32_bf16 v[36:39], v[172:175], v[196:199], v[36:39]
	v_mfma_f32_16x16x32_bf16 v[32:35], v[180:183], v[196:199], v[32:35]
	v_mfma_f32_16x16x32_bf16 v[20:23], v[172:175], v[204:207], v[20:23]
	v_mfma_f32_16x16x32_bf16 v[16:19], v[180:183], v[204:207], v[16:19]
	v_mfma_f32_16x16x32_bf16 v[4:7], v[172:175], v[212:215], v[4:7]
	v_mfma_f32_16x16x32_bf16 v[0:3], v[180:183], v[212:215], v[0:3]
	s_barrier
	s_add_i32 s61, 0, 0x18000
	s_add_i32 s62, 0, 0x1c000
	v_add_u32_e32 v164, s61, v153
	v_add_u32_e32 v180, s62, v153
	ds_read_b128 v[144:147], v164
	ds_read_b128 v[148:151], v164 offset:1024
	ds_read_b128 v[160:163], v164 offset:2048
	ds_read_b128 v[164:167], v164 offset:3072
	ds_read_b128 v[168:171], v180
	ds_read_b128 v[172:175], v180 offset:1024
	ds_read_b128 v[176:179], v180 offset:2048
	ds_read_b128 v[180:183], v180 offset:3072
	s_add_u32 s34, s34, 0x80000
	s_addc_u32 s35, s35, 0
	s_mov_b32 m0, s46
	v_lshl_add_u64 v[224:225], s[34:35], 0, v[134:135]
	ds_read_b128 v[184:187], v157 offset:32768
	ds_read_b128 v[188:191], v157 offset:33792
	ds_read_b128 v[192:195], v157 offset:34816
	ds_read_b128 v[196:199], v157 offset:35840
	ds_read_b128 v[200:203], v157 offset:36864
	ds_read_b128 v[204:207], v157 offset:37888
	ds_read_b128 v[208:211], v157 offset:38912
	ds_read_b128 v[212:215], v157 offset:39936
	global_load_lds_dwordx4 v[224:225], off
	v_lshl_add_u64 v[224:225], s[34:35], 0, v[130:131]
	s_mov_b32 m0, s47
	s_nop 0
	global_load_lds_dwordx4 v[224:225], off
	s_mov_b32 m0, s25
	s_nop 0
	global_load_lds_dwordx4 v[220:221], off
	s_mov_b32 m0, s45
	s_nop 0
	global_load_lds_dwordx4 v[222:223], off
	s_waitcnt vmcnt(10)
	s_waitcnt lgkmcnt(0)
	s_barrier
; #define PG8_STAGE(bufoff, gbase, voff) do { _Pragma("unroll") for (int _i = 0; _i < 2; ++_i) \
;         __builtin_amdgcn_global_load_lds((const unsigned*)((const char*)(gbase) + (voff)[_i]), (PG8_LAS unsigned*)(lds + (bufoff) + ldsw + _i * 8192), 16, 0, 0); } while (0)
; #define PG8_LDA(dst, b, h) do { _Pragma("unroll") for (int m = 0; m < 4; ++m) _Pragma("unroll") for (int k = 0; k < 2; ++k) dst[m][k] = *(const PG8_LAS bf16x8*)(lds + PG8_SA(b, h) + aoff + m * 2048 + k * 1024); } while (0)
; #define PG8_MMA(ai, bj, At, Bt) do { __builtin_amdgcn_s_setprio(1); _Pragma("unroll") for (int m = 0; m < 4; ++m) _Pragma("unroll") for (int n = 0; n < 2; ++n) _Pragma("unroll") for (int k = 0; k < 2; ++k) \
;         acc[ai][bj][m][n] = __builtin_amdgcn_mfma_f32_16x16x32_bf16(Bt[n][k], At[m][k], acc[ai][bj][m][n], 0, 0, 0); __builtin_amdgcn_s_setprio(0); } while (0)
; #define PG8_WAIT_V(n) asm volatile("s_waitcnt vmcnt(" #n ")" ::: "memory")
; #define PG8_WAIT_L(n) asm volatile("s_waitcnt lgkmcnt(" #n ")" ::: "memory")
; #define PG8_BAR __builtin_amdgcn_s_barrier()
; #define PG8_SCHED __builtin_amdgcn_sched_barrier(0)
; template <class Epi, class Sched, bool ALIGN_EPI = false, bool SP2 = false>
; __device__ __forceinline__ void gemm_phase(PG8_LAS unsigned char* lds, const Gemm g, const Sched& S, const Epi& E) {
;     ...
;             PG8_WAIT_V(8); PG8_WAIT_L(0); PG8_BAR; PG8_MMA(0, 0, At, B0); PG8_MMA(0, 1, At, B1); PG8_BAR; PG8_SCHED;
;             PG8_LDA(At, 1, 1); PG8_STAGE(PG8_SB(1, 0), b3, voffB); PG8_STAGE(PG8_SB(1, 1), b3 + hstep, voffB); PG8_STAGE(PG8_SA(1, 0), a3, voffA);
;             PG8_WAIT_V(8); PG8_WAIT_L(0); PG8_BAR; PG8_MMA(1, 0, At, B0); PG8_MMA(1, 1, At, B1); PG8_BAR; PG8_SCHED;
	s_waitcnt lgkmcnt(0)
	v_mfma_f32_16x16x32_bf16 v[124:127], v[144:147], v[184:187], v[124:127]
	v_mfma_f32_16x16x32_bf16 v[120:123], v[160:163], v[184:187], v[120:123]
	s_add_u32 s30, s30, 0x80080
	v_mfma_f32_16x16x32_bf16 v[108:111], v[144:147], v[192:195], v[108:111]
	v_mfma_f32_16x16x32_bf16 v[104:107], v[160:163], v[192:195], v[104:107]
	s_addc_u32 s31, s31, 0
	v_mfma_f32_16x16x32_bf16 v[92:95], v[144:147], v[200:203], v[92:95]
	v_mfma_f32_16x16x32_bf16 v[88:91], v[160:163], v[200:203], v[88:91]
	v_lshl_add_u64 v[216:217], v[216:217], 0, s[8:9]
	v_mfma_f32_16x16x32_bf16 v[76:79], v[144:147], v[208:211], v[76:79]
	v_mfma_f32_16x16x32_bf16 v[72:75], v[160:163], v[208:211], v[72:75]
	v_lshl_add_u64 v[218:219], v[218:219], 0, s[8:9]
	v_mfma_f32_16x16x32_bf16 v[124:127], v[148:151], v[188:191], v[124:127]
	v_mfma_f32_16x16x32_bf16 v[120:123], v[164:167], v[188:191], v[120:123]
	v_lshl_add_u64 v[246:247], s[30:31], 0, v[132:133]
	v_mfma_f32_16x16x32_bf16 v[108:111], v[148:151], v[196:199], v[108:111]
	v_mfma_f32_16x16x32_bf16 v[104:107], v[164:167], v[196:199], v[104:107]
	v_lshl_add_u64 v[248:249], s[30:31], 0, v[128:129]
	v_mfma_f32_16x16x32_bf16 v[92:95], v[148:151], v[204:207], v[92:95]
	v_mfma_f32_16x16x32_bf16 v[88:91], v[164:167], v[204:207], v[88:91]
	v_lshl_add_u64 v[250:251], v[220:221], 0, s[8:9]
	v_mfma_f32_16x16x32_bf16 v[76:79], v[148:151], v[212:215], v[76:79]
	v_mfma_f32_16x16x32_bf16 v[72:75], v[164:167], v[212:215], v[72:75]
	v_lshl_add_u64 v[252:253], v[222:223], 0, s[8:9]
	v_mfma_f32_16x16x32_bf16 v[116:119], v[168:171], v[184:187], v[116:119]
	v_mfma_f32_16x16x32_bf16 v[112:115], v[176:179], v[184:187], v[112:115]
	v_mfma_f32_16x16x32_bf16 v[100:103], v[168:171], v[192:195], v[100:103]
	v_mfma_f32_16x16x32_bf16 v[96:99], v[176:179], v[192:195], v[96:99]
	v_mfma_f32_16x16x32_bf16 v[84:87], v[168:171], v[200:203], v[84:87]
	v_mfma_f32_16x16x32_bf16 v[80:83], v[176:179], v[200:203], v[80:83]
	v_mfma_f32_16x16x32_bf16 v[68:71], v[168:171], v[208:211], v[68:71]
	v_mfma_f32_16x16x32_bf16 v[64:67], v[176:179], v[208:211], v[64:67]
	v_mfma_f32_16x16x32_bf16 v[116:119], v[172:175], v[188:191], v[116:119]
	v_mfma_f32_16x16x32_bf16 v[112:115], v[180:183], v[188:191], v[112:115]
	v_mfma_f32_16x16x32_bf16 v[100:103], v[172:175], v[196:199], v[100:103]
	v_mfma_f32_16x16x32_bf16 v[96:99], v[180:183], v[196:199], v[96:99]
	v_mfma_f32_16x16x32_bf16 v[84:87], v[172:175], v[204:207], v[84:87]
	v_mfma_f32_16x16x32_bf16 v[80:83], v[180:183], v[204:207], v[80:83]
	v_mfma_f32_16x16x32_bf16 v[68:71], v[172:175], v[212:215], v[68:71]
	v_mfma_f32_16x16x32_bf16 v[64:67], v[180:183], v[212:215], v[64:67]
	s_add_i32 s34, s61, s42
	s_mov_b32 m0, s34
	s_barrier
	global_load_lds_dwordx4 v[216:217], off
	s_add_i32 m0, s34, 0x2000
	s_add_i32 s34, s62, s42
	global_load_lds_dwordx4 v[218:219], off
	s_mov_b32 m0, s34
	s_nop 0
	global_load_lds_dwordx4 v[246:247], off
	s_add_i32 m0, s34, 0x2000
	s_nop 0
	global_load_lds_dwordx4 v[248:249], off
	ds_read_b128 v[184:187], v157 offset:49152
	ds_read_b128 v[188:191], v157 offset:50176
	ds_read_b128 v[192:195], v157 offset:51200
	ds_read_b128 v[196:199], v157 offset:52224
	ds_read_b128 v[200:203], v157 offset:53248
	ds_read_b128 v[204:207], v157 offset:54272
	ds_read_b128 v[208:211], v157 offset:55296
	ds_read_b128 v[212:215], v157 offset:56320
	s_waitcnt vmcnt(4)
	s_waitcnt lgkmcnt(0)
	s_barrier
	s_waitcnt lgkmcnt(0)
	v_mfma_f32_16x16x32_bf16 v[60:63], v[144:147], v[184:187], v[60:63]
	v_mfma_f32_16x16x32_bf16 v[56:59], v[160:163], v[184:187], v[56:59]
	v_mfma_f32_16x16x32_bf16 v[44:47], v[144:147], v[192:195], v[44:47]
	v_mfma_f32_16x16x32_bf16 v[40:43], v[160:163], v[192:195], v[40:43]
	v_mfma_f32_16x16x32_bf16 v[28:31], v[144:147], v[200:203], v[28:31]
	v_mfma_f32_16x16x32_bf16 v[24:27], v[160:163], v[200:203], v[24:27]
	v_mfma_f32_16x16x32_bf16 v[12:15], v[144:147], v[208:211], v[12:15]
	v_mfma_f32_16x16x32_bf16 v[8:11], v[160:163], v[208:211], v[8:11]
	v_mfma_f32_16x16x32_bf16 v[60:63], v[148:151], v[188:191], v[60:63]
	v_mfma_f32_16x16x32_bf16 v[56:59], v[164:167], v[188:191], v[56:59]
	v_mfma_f32_16x16x32_bf16 v[44:47], v[148:151], v[196:199], v[44:47]
	v_mfma_f32_16x16x32_bf16 v[40:43], v[164:167], v[196:199], v[40:43]
	v_mfma_f32_16x16x32_bf16 v[28:31], v[148:151], v[204:207], v[28:31]
	v_mfma_f32_16x16x32_bf16 v[24:27], v[164:167], v[204:207], v[24:27]
	v_mfma_f32_16x16x32_bf16 v[12:15], v[148:151], v[212:215], v[12:15]
	v_mfma_f32_16x16x32_bf16 v[8:11], v[164:167], v[212:215], v[8:11]
	v_mfma_f32_16x16x32_bf16 v[52:55], v[168:171], v[184:187], v[52:55]
	v_mfma_f32_16x16x32_bf16 v[48:51], v[176:179], v[184:187], v[48:51]
	v_mfma_f32_16x16x32_bf16 v[36:39], v[168:171], v[192:195], v[36:39]
	v_mfma_f32_16x16x32_bf16 v[32:35], v[176:179], v[192:195], v[32:35]
	s_add_i32 s60, s60, 2
	v_mfma_f32_16x16x32_bf16 v[20:23], v[168:171], v[200:203], v[20:23]
	v_mfma_f32_16x16x32_bf16 v[16:19], v[176:179], v[200:203], v[16:19]
	s_add_u32 s28, s28, 0x100
	v_mfma_f32_16x16x32_bf16 v[4:7], v[168:171], v[208:211], v[4:7]
	v_mfma_f32_16x16x32_bf16 v[0:3], v[176:179], v[208:211], v[0:3]
	s_addc_u32 s29, s29, 0
	v_mfma_f32_16x16x32_bf16 v[52:55], v[172:175], v[188:191], v[52:55]
	v_mfma_f32_16x16x32_bf16 v[48:51], v[180:183], v[188:191], v[48:51]
	s_add_u32 s58, s58, 0x100
	v_mfma_f32_16x16x32_bf16 v[36:39], v[172:175], v[196:199], v[36:39]
	v_mfma_f32_16x16x32_bf16 v[32:35], v[180:183], v[196:199], v[32:35]
	s_addc_u32 s59, s59, 0
	v_mfma_f32_16x16x32_bf16 v[20:23], v[172:175], v[204:207], v[20:23]
	v_mfma_f32_16x16x32_bf16 v[16:19], v[180:183], v[204:207], v[16:19]
	v_mfma_f32_16x16x32_bf16 v[4:7], v[172:175], v[212:215], v[4:7]
	v_mfma_f32_16x16x32_bf16 v[0:3], v[180:183], v[212:215], v[0:3]
	s_barrier
	s_cmp_gt_u32 s60, 29
	s_cbranch_scc0 .LBB0_150
	s_and_b64 vcc, exec, s[10:11]
	s_cbranch_vccz .LBB0_153
	s_barrier

; #define PG8_STAGE(bufoff, gbase, voff) do { _Pragma("unroll") for (int _i = 0; _i < 2; ++_i) \
;         __builtin_amdgcn_global_load_lds((const unsigned*)((const char*)(gbase) + (voff)[_i]), (PG8_LAS unsigned*)(lds + (bufoff) + ldsw + _i * 8192), 16, 0, 0); } while (0)
; #define PG8_LDA(dst, b, h) do { _Pragma("unroll") for (int m = 0; m < 4; ++m) _Pragma("unroll") for (int k = 0; k < 2; ++k) dst[m][k] = *(const PG8_LAS bf16x8*)(lds + PG8_SA(b, h) + aoff + m * 2048 + k * 1024); } while (0)
; #define PG8_LDB(dst, b, h) do { _Pragma("unroll") for (int n = 0; n < 2; ++n) _Pragma("unroll") for (int k = 0; k < 2; ++k) dst[n][k] = *(const PG8_LAS bf16x8*)(lds + PG8_SB(b, h) + boff + n * 2048 + k * 1024); } while (0)
; #define PG8_MMA(ai, bj, At, Bt) do { __builtin_amdgcn_s_setprio(1); _Pragma("unroll") for (int m = 0; m < 4; ++m) _Pragma("unroll") for (int n = 0; n < 2; ++n) _Pragma("unroll") for (int k = 0; k < 2; ++k) \
;         acc[ai][bj][m][n] = __builtin_amdgcn_mfma_f32_16x16x32_bf16(Bt[n][k], At[m][k], acc[ai][bj][m][n], 0, 0, 0); __builtin_amdgcn_s_setprio(0); } while (0)
; #define PG8_WAIT_V(n) asm volatile("s_waitcnt vmcnt(" #n ")" ::: "memory")
; #define PG8_WAIT_L(n) asm volatile("s_waitcnt lgkmcnt(" #n ")" ::: "memory")
; template <class Epi, class Sched, bool ALIGN_EPI = false, bool SP2 = false>
; __device__ __forceinline__ void gemm_phase(PG8_LAS unsigned char* lds, const Gemm g, const Sched& S, const Epi& E) {
;     ...
;             const bool last = (t == nt - 2);
;             const char* a1 = cA + (size_t)(t + 1) * kstep;
;             const char* a2 = last ? nA : cA + (size_t)(t + 2) * kstep; const char* b2 = last ? nB : cB + (size_t)(t + 2) * kstep;
;             const char* a3 = a2 + kstep; const char* b3 = b2 + kstep;
;             if (last && has_next) S.a_ready(nxt);
;             if constexpr (SP2) {
;             PG8_LDB(B0, 0, 0); PG8_LDB(B1, 0, 1); PG8_SCHED; PG8_LDA(At, 0, 0); PG8_STAGE(PG8_SA(1, 1), a1 + hstep, voffA);
;             PG8_WAIT_V(8); PG8_WAIT_L(0); PG8_BAR; PG8_MMA(0, 0, At, B0); PG8_MMA(0, 1, At, B1); PG8_BAR; PG8_SCHED;
;             PG8_LDA(At, 0, 1); PG8_STAGE(PG8_SB(0, 0), b2, voffB); PG8_STAGE(PG8_SB(0, 1), b2 + hstep, voffB); PG8_STAGE(PG8_SA(0, 0), a2, voffA);
;             PG8_WAIT_V(8); PG8_WAIT_L(0); PG8_BAR; PG8_MMA(1, 0, At, B0); PG8_MMA(1, 1, At, B1); PG8_BAR; PG8_SCHED;
.LBB0_621:
	ds_read_b128 v[128:131], v189
	ds_read_b128 v[132:135], v189 offset:1024
	ds_read_b128 v[136:139], v189 offset:2048
	ds_read_b128 v[140:143], v189 offset:3072
	ds_read_b128 v[144:147], v190
	ds_read_b128 v[148:151], v190 offset:1024
	ds_read_b128 v[168:171], v190 offset:2048
	ds_read_b128 v[172:175], v190 offset:3072
	s_add_u32 s36, s34, 0xfff80080
	s_addc_u32 s37, s35, -1
	s_cmp_eq_u32 s60, 28
	s_cselect_b32 s39, s17, s37
	s_cselect_b32 s38, s29, s36
	s_cselect_b32 s37, s15, s59
	s_cselect_b32 s36, s57, s58
	v_lshl_add_u64 v[184:185], s[34:35], 0, v[160:161]
	s_add_i32 m0, s31, 0xc000
	ds_read_b128 v[176:179], v191
	ds_read_b128 v[180:183], v191 offset:1024
	ds_read_b128 v[192:195], v191 offset:2048
	ds_read_b128 v[196:199], v191 offset:3072
	ds_read_b128 v[200:203], v191 offset:4096
	ds_read_b128 v[204:207], v191 offset:5120
	ds_read_b128 v[208:211], v191 offset:6144
	ds_read_b128 v[212:215], v191 offset:7168
	global_load_lds_dwordx4 v[184:185], off
	v_lshl_add_u64 v[184:185], s[34:35], 0, v[162:163]
	s_add_i32 m0, s31, 0xe000
	s_nop 0
	global_load_lds_dwordx4 v[184:185], off
	s_mov_b32 m0, s50
	s_nop 0
	global_load_lds_dwordx4 v[250:251], off
	s_mov_b32 m0, s51
	s_nop 0
	global_load_lds_dwordx4 v[252:253], off
	s_waitcnt vmcnt(10)
	s_waitcnt lgkmcnt(0)
	s_barrier
	s_waitcnt lgkmcnt(0)
	v_mfma_f32_16x16x32_bf16 v[124:127], v[128:131], v[176:179], v[124:127]
	v_mfma_f32_16x16x32_bf16 v[120:123], v[136:139], v[176:179], v[120:123]
	s_add_u32 s62, s36, 0x80000
	v_mfma_f32_16x16x32_bf16 v[108:111], v[128:131], v[192:195], v[108:111]
	v_mfma_f32_16x16x32_bf16 v[104:107], v[136:139], v[192:195], v[104:107]
	s_addc_u32 s63, s37, 0
	v_mfma_f32_16x16x32_bf16 v[92:95], v[128:131], v[200:203], v[92:95]
	v_mfma_f32_16x16x32_bf16 v[88:91], v[136:139], v[200:203], v[88:91]
	v_lshl_add_u64 v[184:185], s[36:37], 0, v[154:155]
	v_mfma_f32_16x16x32_bf16 v[76:79], v[128:131], v[208:211], v[76:79]
	v_mfma_f32_16x16x32_bf16 v[72:75], v[136:139], v[208:211], v[72:75]
	v_lshl_add_u64 v[216:217], s[36:37], 0, v[158:159]
	v_mfma_f32_16x16x32_bf16 v[124:127], v[132:135], v[180:183], v[124:127]
	v_mfma_f32_16x16x32_bf16 v[120:123], v[140:143], v[180:183], v[120:123]
	v_lshl_add_u64 v[246:247], s[62:63], 0, v[154:155]
	v_mfma_f32_16x16x32_bf16 v[108:111], v[132:135], v[196:199], v[108:111]
	v_mfma_f32_16x16x32_bf16 v[104:107], v[140:143], v[196:199], v[104:107]
	v_lshl_add_u64 v[220:221], s[38:39], 0, v[156:157]
	v_mfma_f32_16x16x32_bf16 v[92:95], v[132:135], v[204:207], v[92:95]
	v_mfma_f32_16x16x32_bf16 v[88:91], v[140:143], v[204:207], v[88:91]
	v_lshl_add_u64 v[248:249], s[62:63], 0, v[158:159]
	v_mfma_f32_16x16x32_bf16 v[76:79], v[132:135], v[212:215], v[76:79]
	v_mfma_f32_16x16x32_bf16 v[72:75], v[140:143], v[212:215], v[72:75]
	v_lshl_add_u64 v[218:219], s[38:39], 0, v[152:153]
	v_mfma_f32_16x16x32_bf16 v[116:119], v[144:147], v[176:179], v[116:119]
	v_mfma_f32_16x16x32_bf16 v[112:115], v[168:171], v[176:179], v[112:115]
	v_mfma_f32_16x16x32_bf16 v[100:103], v[144:147], v[192:195], v[100:103]
	v_mfma_f32_16x16x32_bf16 v[96:99], v[168:171], v[192:195], v[96:99]
	v_mfma_f32_16x16x32_bf16 v[84:87], v[144:147], v[200:203], v[84:87]
	v_mfma_f32_16x16x32_bf16 v[80:83], v[168:171], v[200:203], v[80:83]
	v_mfma_f32_16x16x32_bf16 v[68:71], v[144:147], v[208:211], v[68:71]
	v_mfma_f32_16x16x32_bf16 v[64:67], v[168:171], v[208:211], v[64:67]
	v_mfma_f32_16x16x32_bf16 v[116:119], v[148:151], v[180:183], v[116:119]
	v_mfma_f32_16x16x32_bf16 v[112:115], v[172:175], v[180:183], v[112:115]
	v_mfma_f32_16x16x32_bf16 v[100:103], v[148:151], v[196:199], v[100:103]
	v_mfma_f32_16x16x32_bf16 v[96:99], v[172:175], v[196:199], v[96:99]
	v_mfma_f32_16x16x32_bf16 v[84:87], v[148:151], v[204:207], v[84:87]
	v_mfma_f32_16x16x32_bf16 v[80:83], v[172:175], v[204:207], v[80:83]
	v_mfma_f32_16x16x32_bf16 v[68:71], v[148:151], v[212:215], v[68:71]
	v_mfma_f32_16x16x32_bf16 v[64:67], v[172:175], v[212:215], v[64:67]
	s_add_i32 s61, s54, s45
	s_mov_b32 m0, s61
	s_barrier
	global_load_lds_dwordx4 v[184:185], off
	s_add_i32 m0, s61, 0x2000
	s_add_i32 s61, s55, s45
	global_load_lds_dwordx4 v[216:217], off
	s_mov_b32 m0, s61
	s_nop 0
	global_load_lds_dwordx4 v[246:247], off
	s_add_i32 m0, s61, 0x2000
	s_nop 0
	global_load_lds_dwordx4 v[248:249], off
	ds_read_b128 v[176:179], v191 offset:16384
	ds_read_b128 v[180:183], v191 offset:17408
	ds_read_b128 v[192:195], v191 offset:18432
	ds_read_b128 v[196:199], v191 offset:19456
	ds_read_b128 v[200:203], v191 offset:20480
	ds_read_b128 v[204:207], v191 offset:21504
	ds_read_b128 v[208:211], v191 offset:22528
	ds_read_b128 v[212:215], v191 offset:23552
	s_waitcnt vmcnt(4)
	s_waitcnt lgkmcnt(0)
	s_barrier
; #define PG8_STAGE(bufoff, gbase, voff) do { _Pragma("unroll") for (int _i = 0; _i < 2; ++_i) \
;         __builtin_amdgcn_global_load_lds((const unsigned*)((const char*)(gbase) + (voff)[_i]), (PG8_LAS unsigned*)(lds + (bufoff) + ldsw + _i * 8192), 16, 0, 0); } while (0)
; #define PG8_LDA(dst, b, h) do { _Pragma("unroll") for (int m = 0; m < 4; ++m) _Pragma("unroll") for (int k = 0; k < 2; ++k) dst[m][k] = *(const PG8_LAS bf16x8*)(lds + PG8_SA(b, h) + aoff + m * 2048 + k * 1024); } while (0)
; #define PG8_LDB(dst, b, h) do { _Pragma("unroll") for (int n = 0; n < 2; ++n) _Pragma("unroll") for (int k = 0; k < 2; ++k) dst[n][k] = *(const PG8_LAS bf16x8*)(lds + PG8_SB(b, h) + boff + n * 2048 + k * 1024); } while (0)
; #define PG8_MMA(ai, bj, At, Bt) do { __builtin_amdgcn_s_setprio(1); _Pragma("unroll") for (int m = 0; m < 4; ++m) _Pragma("unroll") for (int n = 0; n < 2; ++n) _Pragma("unroll") for (int k = 0; k < 2; ++k) \
;         acc[ai][bj][m][n] = __builtin_amdgcn_mfma_f32_16x16x32_bf16(Bt[n][k], At[m][k], acc[ai][bj][m][n], 0, 0, 0); __builtin_amdgcn_s_setprio(0); } while (0)
; #define PG8_WAIT_V(n) asm volatile("s_waitcnt vmcnt(" #n ")" ::: "memory")
; #define PG8_WAIT_L(n) asm volatile("s_waitcnt lgkmcnt(" #n ")" ::: "memory")
; #define PG8_BAR __builtin_amdgcn_s_barrier()
; #define PG8_SCHED __builtin_amdgcn_sched_barrier(0)
; template <class Epi, class Sched, bool ALIGN_EPI = false, bool SP2 = false>
; __device__ __forceinline__ void gemm_phase(PG8_LAS unsigned char* lds, const Gemm g, const Sched& S, const Epi& E) {
;     ...
;             PG8_WAIT_V(8); PG8_WAIT_L(0); PG8_BAR; PG8_MMA(1, 0, At, B0); PG8_MMA(1, 1, At, B1); PG8_BAR; PG8_SCHED;
;             PG8_LDB(B0, 1, 0); PG8_LDB(B1, 1, 1); PG8_SCHED; PG8_LDA(At, 1, 0); PG8_STAGE(PG8_SA(0, 1), a2 + hstep, voffA);
;             PG8_WAIT_V(8); PG8_WAIT_L(0); PG8_BAR; PG8_MMA(0, 0, At, B0); PG8_MMA(0, 1, At, B1); PG8_BAR; PG8_SCHED;
	s_waitcnt lgkmcnt(0)
	v_mfma_f32_16x16x32_bf16 v[60:63], v[128:131], v[176:179], v[60:63]
	v_mfma_f32_16x16x32_bf16 v[56:59], v[136:139], v[176:179], v[56:59]
	v_mfma_f32_16x16x32_bf16 v[44:47], v[128:131], v[192:195], v[44:47]
	v_mfma_f32_16x16x32_bf16 v[40:43], v[136:139], v[192:195], v[40:43]
	v_mfma_f32_16x16x32_bf16 v[28:31], v[128:131], v[200:203], v[28:31]
	v_mfma_f32_16x16x32_bf16 v[24:27], v[136:139], v[200:203], v[24:27]
	v_mfma_f32_16x16x32_bf16 v[12:15], v[128:131], v[208:211], v[12:15]
	v_mfma_f32_16x16x32_bf16 v[8:11], v[136:139], v[208:211], v[8:11]
	v_mfma_f32_16x16x32_bf16 v[60:63], v[132:135], v[180:183], v[60:63]
	v_mfma_f32_16x16x32_bf16 v[56:59], v[140:143], v[180:183], v[56:59]
	v_mfma_f32_16x16x32_bf16 v[44:47], v[132:135], v[196:199], v[44:47]
	v_mfma_f32_16x16x32_bf16 v[40:43], v[140:143], v[196:199], v[40:43]
	v_mfma_f32_16x16x32_bf16 v[28:31], v[132:135], v[204:207], v[28:31]
	v_mfma_f32_16x16x32_bf16 v[24:27], v[140:143], v[204:207], v[24:27]
	v_mfma_f32_16x16x32_bf16 v[12:15], v[132:135], v[212:215], v[12:15]
	v_mfma_f32_16x16x32_bf16 v[8:11], v[140:143], v[212:215], v[8:11]
	v_mfma_f32_16x16x32_bf16 v[52:55], v[144:147], v[176:179], v[52:55]
	v_mfma_f32_16x16x32_bf16 v[48:51], v[168:171], v[176:179], v[48:51]
	v_mfma_f32_16x16x32_bf16 v[36:39], v[144:147], v[192:195], v[36:39]
	v_mfma_f32_16x16x32_bf16 v[32:35], v[168:171], v[192:195], v[32:35]
	v_mfma_f32_16x16x32_bf16 v[20:23], v[144:147], v[200:203], v[20:23]
	v_mfma_f32_16x16x32_bf16 v[16:19], v[168:171], v[200:203], v[16:19]
	v_mfma_f32_16x16x32_bf16 v[4:7], v[144:147], v[208:211], v[4:7]
	v_mfma_f32_16x16x32_bf16 v[0:3], v[168:171], v[208:211], v[0:3]
	v_mfma_f32_16x16x32_bf16 v[52:55], v[148:151], v[180:183], v[52:55]
	v_mfma_f32_16x16x32_bf16 v[48:51], v[172:175], v[180:183], v[48:51]
	v_mfma_f32_16x16x32_bf16 v[36:39], v[148:151], v[196:199], v[36:39]
	v_mfma_f32_16x16x32_bf16 v[32:35], v[172:175], v[196:199], v[32:35]
	v_mfma_f32_16x16x32_bf16 v[20:23], v[148:151], v[204:207], v[20:23]
	v_mfma_f32_16x16x32_bf16 v[16:19], v[172:175], v[204:207], v[16:19]
	v_mfma_f32_16x16x32_bf16 v[4:7], v[148:151], v[212:215], v[4:7]
	v_mfma_f32_16x16x32_bf16 v[0:3], v[172:175], v[212:215], v[0:3]
	s_barrier
	s_add_i32 s61, 0, 0x18000
	s_add_i32 s62, 0, 0x1c000
	v_add_u32_e32 v140, s61, v187
	v_add_u32_e32 v172, s62, v187
	ds_read_b128 v[128:131], v140
	ds_read_b128 v[132:135], v140 offset:1024
	ds_read_b128 v[136:139], v140 offset:2048
	ds_read_b128 v[140:143], v140 offset:3072
	ds_read_b128 v[144:147], v172
	ds_read_b128 v[148:151], v172 offset:1024
	ds_read_b128 v[168:171], v172 offset:2048
	ds_read_b128 v[172:175], v172 offset:3072
	s_add_u32 s38, s38, 0x80000
	s_addc_u32 s39, s39, 0
	s_mov_b32 m0, s47
	v_lshl_add_u64 v[222:223], s[38:39], 0, v[152:153]
	ds_read_b128 v[176:179], v191 offset:32768
	ds_read_b128 v[180:183], v191 offset:33792
	ds_read_b128 v[192:195], v191 offset:34816
	ds_read_b128 v[196:199], v191 offset:35840
	ds_read_b128 v[200:203], v191 offset:36864
	ds_read_b128 v[204:207], v191 offset:37888
	ds_read_b128 v[208:211], v191 offset:38912
	ds_read_b128 v[212:215], v191 offset:39936
	global_load_lds_dwordx4 v[222:223], off
	v_lshl_add_u64 v[222:223], s[38:39], 0, v[156:157]
	s_mov_b32 m0, s48
	s_nop 0
	global_load_lds_dwordx4 v[222:223], off
	s_mov_b32 m0, s31
	s_nop 0
	global_load_lds_dwordx4 v[218:219], off
	s_mov_b32 m0, s46
	s_nop 0
	global_load_lds_dwordx4 v[220:221], off
	s_waitcnt vmcnt(10)
	s_waitcnt lgkmcnt(0)
	s_barrier
; #define PG8_STAGE(bufoff, gbase, voff) do { _Pragma("unroll") for (int _i = 0; _i < 2; ++_i) \
;         __builtin_amdgcn_global_load_lds((const unsigned*)((const char*)(gbase) + (voff)[_i]), (PG8_LAS unsigned*)(lds + (bufoff) + ldsw + _i * 8192), 16, 0, 0); } while (0)
; #define PG8_LDA(dst, b, h) do { _Pragma("unroll") for (int m = 0; m < 4; ++m) _Pragma("unroll") for (int k = 0; k < 2; ++k) dst[m][k] = *(const PG8_LAS bf16x8*)(lds + PG8_SA(b, h) + aoff + m * 2048 + k * 1024); } while (0)
; #define PG8_MMA(ai, bj, At, Bt) do { __builtin_amdgcn_s_setprio(1); _Pragma("unroll") for (int m = 0; m < 4; ++m) _Pragma("unroll") for (int n = 0; n < 2; ++n) _Pragma("unroll") for (int k = 0; k < 2; ++k) \
;         acc[ai][bj][m][n] = __builtin_amdgcn_mfma_f32_16x16x32_bf16(Bt[n][k], At[m][k], acc[ai][bj][m][n], 0, 0, 0); __builtin_amdgcn_s_setprio(0); } while (0)
; #define PG8_WAIT_V(n) asm volatile("s_waitcnt vmcnt(" #n ")" ::: "memory")
; #define PG8_WAIT_L(n) asm volatile("s_waitcnt lgkmcnt(" #n ")" ::: "memory")
; #define PG8_BAR __builtin_amdgcn_s_barrier()
; #define PG8_SCHED __builtin_amdgcn_sched_barrier(0)
; template <class Epi, class Sched, bool ALIGN_EPI = false, bool SP2 = false>
; __device__ __forceinline__ void gemm_phase(PG8_LAS unsigned char* lds, const Gemm g, const Sched& S, const Epi& E) {
;     ...
;             PG8_WAIT_V(8); PG8_WAIT_L(0); PG8_BAR; PG8_MMA(0, 0, At, B0); PG8_MMA(0, 1, At, B1); PG8_BAR; PG8_SCHED;
;             PG8_LDA(At, 1, 1); PG8_STAGE(PG8_SB(1, 0), b3, voffB); PG8_STAGE(PG8_SB(1, 1), b3 + hstep, voffB); PG8_STAGE(PG8_SA(1, 0), a3, voffA);
;             PG8_WAIT_V(8); PG8_WAIT_L(0); PG8_BAR; PG8_MMA(1, 0, At, B0); PG8_MMA(1, 1, At, B1); PG8_BAR; PG8_SCHED;
	s_waitcnt lgkmcnt(0)
	v_mfma_f32_16x16x32_bf16 v[124:127], v[128:131], v[176:179], v[124:127]
	v_mfma_f32_16x16x32_bf16 v[120:123], v[136:139], v[176:179], v[120:123]
	s_add_u32 s36, s36, 0x80080
	v_mfma_f32_16x16x32_bf16 v[108:111], v[128:131], v[192:195], v[108:111]
	v_mfma_f32_16x16x32_bf16 v[104:107], v[136:139], v[192:195], v[104:107]
	s_addc_u32 s37, s37, 0
	v_mfma_f32_16x16x32_bf16 v[92:95], v[128:131], v[200:203], v[92:95]
	v_mfma_f32_16x16x32_bf16 v[88:91], v[136:139], v[200:203], v[88:91]
	v_lshl_add_u64 v[184:185], v[184:185], 0, s[10:11]
	v_mfma_f32_16x16x32_bf16 v[76:79], v[128:131], v[208:211], v[76:79]
	v_mfma_f32_16x16x32_bf16 v[72:75], v[136:139], v[208:211], v[72:75]
	v_lshl_add_u64 v[216:217], v[216:217], 0, s[10:11]
	v_mfma_f32_16x16x32_bf16 v[124:127], v[132:135], v[180:183], v[124:127]
	v_mfma_f32_16x16x32_bf16 v[120:123], v[140:143], v[180:183], v[120:123]
	v_lshl_add_u64 v[246:247], s[36:37], 0, v[154:155]
	v_mfma_f32_16x16x32_bf16 v[108:111], v[132:135], v[196:199], v[108:111]
	v_mfma_f32_16x16x32_bf16 v[104:107], v[140:143], v[196:199], v[104:107]
	v_lshl_add_u64 v[248:249], s[36:37], 0, v[158:159]
	v_mfma_f32_16x16x32_bf16 v[92:95], v[132:135], v[204:207], v[92:95]
	v_mfma_f32_16x16x32_bf16 v[88:91], v[140:143], v[204:207], v[88:91]
	v_lshl_add_u64 v[250:251], v[218:219], 0, s[10:11]
	v_mfma_f32_16x16x32_bf16 v[76:79], v[132:135], v[212:215], v[76:79]
	v_mfma_f32_16x16x32_bf16 v[72:75], v[140:143], v[212:215], v[72:75]
	v_lshl_add_u64 v[252:253], v[220:221], 0, s[10:11]
	v_mfma_f32_16x16x32_bf16 v[116:119], v[144:147], v[176:179], v[116:119]
	v_mfma_f32_16x16x32_bf16 v[112:115], v[168:171], v[176:179], v[112:115]
	v_mfma_f32_16x16x32_bf16 v[100:103], v[144:147], v[192:195], v[100:103]
	v_mfma_f32_16x16x32_bf16 v[96:99], v[168:171], v[192:195], v[96:99]
	v_mfma_f32_16x16x32_bf16 v[84:87], v[144:147], v[200:203], v[84:87]
	v_mfma_f32_16x16x32_bf16 v[80:83], v[168:171], v[200:203], v[80:83]
	v_mfma_f32_16x16x32_bf16 v[68:71], v[144:147], v[208:211], v[68:71]
	v_mfma_f32_16x16x32_bf16 v[64:67], v[168:171], v[208:211], v[64:67]
	v_mfma_f32_16x16x32_bf16 v[116:119], v[148:151], v[180:183], v[116:119]
	v_mfma_f32_16x16x32_bf16 v[112:115], v[172:175], v[180:183], v[112:115]
	v_mfma_f32_16x16x32_bf16 v[100:103], v[148:151], v[196:199], v[100:103]
	v_mfma_f32_16x16x32_bf16 v[96:99], v[172:175], v[196:199], v[96:99]
	v_mfma_f32_16x16x32_bf16 v[84:87], v[148:151], v[204:207], v[84:87]
	v_mfma_f32_16x16x32_bf16 v[80:83], v[172:175], v[204:207], v[80:83]
	v_mfma_f32_16x16x32_bf16 v[68:71], v[148:151], v[212:215], v[68:71]
	v_mfma_f32_16x16x32_bf16 v[64:67], v[172:175], v[212:215], v[64:67]
	s_add_i32 s38, s61, s45
	s_mov_b32 m0, s38
	s_barrier
	global_load_lds_dwordx4 v[184:185], off
	s_add_i32 m0, s38, 0x2000
	s_add_i32 s38, s62, s45
	global_load_lds_dwordx4 v[216:217], off
	s_mov_b32 m0, s38
	s_nop 0
	global_load_lds_dwordx4 v[246:247], off
	s_add_i32 m0, s38, 0x2000
	s_nop 0
	global_load_lds_dwordx4 v[248:249], off
	ds_read_b128 v[176:179], v191 offset:49152
	ds_read_b128 v[180:183], v191 offset:50176
	ds_read_b128 v[192:195], v191 offset:51200
	ds_read_b128 v[196:199], v191 offset:52224
	ds_read_b128 v[200:203], v191 offset:53248
	ds_read_b128 v[204:207], v191 offset:54272
	ds_read_b128 v[208:211], v191 offset:55296
	ds_read_b128 v[212:215], v191 offset:56320
	s_waitcnt vmcnt(4)
	s_waitcnt lgkmcnt(0)
	s_barrier
	s_waitcnt lgkmcnt(0)
	v_mfma_f32_16x16x32_bf16 v[60:63], v[128:131], v[176:179], v[60:63]
	v_mfma_f32_16x16x32_bf16 v[56:59], v[136:139], v[176:179], v[56:59]
	v_mfma_f32_16x16x32_bf16 v[44:47], v[128:131], v[192:195], v[44:47]
	v_mfma_f32_16x16x32_bf16 v[40:43], v[136:139], v[192:195], v[40:43]
	v_mfma_f32_16x16x32_bf16 v[28:31], v[128:131], v[200:203], v[28:31]
	v_mfma_f32_16x16x32_bf16 v[24:27], v[136:139], v[200:203], v[24:27]
	v_mfma_f32_16x16x32_bf16 v[12:15], v[128:131], v[208:211], v[12:15]
	v_mfma_f32_16x16x32_bf16 v[8:11], v[136:139], v[208:211], v[8:11]
	v_mfma_f32_16x16x32_bf16 v[60:63], v[132:135], v[180:183], v[60:63]
	v_mfma_f32_16x16x32_bf16 v[56:59], v[140:143], v[180:183], v[56:59]
	v_mfma_f32_16x16x32_bf16 v[44:47], v[132:135], v[196:199], v[44:47]
	v_mfma_f32_16x16x32_bf16 v[40:43], v[140:143], v[196:199], v[40:43]
	v_mfma_f32_16x16x32_bf16 v[28:31], v[132:135], v[204:207], v[28:31]
	v_mfma_f32_16x16x32_bf16 v[24:27], v[140:143], v[204:207], v[24:27]
	v_mfma_f32_16x16x32_bf16 v[12:15], v[132:135], v[212:215], v[12:15]
	v_mfma_f32_16x16x32_bf16 v[8:11], v[140:143], v[212:215], v[8:11]
	v_mfma_f32_16x16x32_bf16 v[52:55], v[144:147], v[176:179], v[52:55]
	v_mfma_f32_16x16x32_bf16 v[48:51], v[168:171], v[176:179], v[48:51]
	v_mfma_f32_16x16x32_bf16 v[36:39], v[144:147], v[192:195], v[36:39]
	v_mfma_f32_16x16x32_bf16 v[32:35], v[168:171], v[192:195], v[32:35]
	s_add_i32 s60, s60, 2
	v_mfma_f32_16x16x32_bf16 v[20:23], v[144:147], v[200:203], v[20:23]
	v_mfma_f32_16x16x32_bf16 v[16:19], v[168:171], v[200:203], v[16:19]
	s_add_u32 s34, s34, 0x100
	v_mfma_f32_16x16x32_bf16 v[4:7], v[144:147], v[208:211], v[4:7]
	v_mfma_f32_16x16x32_bf16 v[0:3], v[168:171], v[208:211], v[0:3]
	s_addc_u32 s35, s35, 0
	v_mfma_f32_16x16x32_bf16 v[52:55], v[148:151], v[180:183], v[52:55]
	v_mfma_f32_16x16x32_bf16 v[48:51], v[172:175], v[180:183], v[48:51]
	s_add_u32 s58, s58, 0x100
	v_mfma_f32_16x16x32_bf16 v[36:39], v[148:151], v[196:199], v[36:39]
	v_mfma_f32_16x16x32_bf16 v[32:35], v[172:175], v[196:199], v[32:35]
	s_addc_u32 s59, s59, 0
	v_mfma_f32_16x16x32_bf16 v[20:23], v[148:151], v[204:207], v[20:23]
	v_mfma_f32_16x16x32_bf16 v[16:19], v[172:175], v[204:207], v[16:19]
	v_mfma_f32_16x16x32_bf16 v[4:7], v[148:151], v[212:215], v[4:7]
	v_mfma_f32_16x16x32_bf16 v[0:3], v[172:175], v[212:215], v[0:3]
	s_barrier
	s_cmp_gt_u32 s60, 29
	s_cbranch_scc0 .LBB0_621
	s_and_b64 vcc, exec, s[12:13]
	s_cbranch_vccz .LBB0_624
	s_barrier

; #define PG8_STAGE(bufoff, gbase, voff) do { _Pragma("unroll") for (int _i = 0; _i < 2; ++_i) \
;         __builtin_amdgcn_global_load_lds((const unsigned*)((const char*)(gbase) + (voff)[_i]), (PG8_LAS unsigned*)(lds + (bufoff) + ldsw + _i * 8192), 16, 0, 0); } while (0)
; #define PG8_LDA(dst, b, h) do { _Pragma("unroll") for (int m = 0; m < 4; ++m) _Pragma("unroll") for (int k = 0; k < 2; ++k) dst[m][k] = *(const PG8_LAS bf16x8*)(lds + PG8_SA(b, h) + aoff + m * 2048 + k * 1024); } while (0)
; #define PG8_LDB(dst, b, h) do { _Pragma("unroll") for (int n = 0; n < 2; ++n) _Pragma("unroll") for (int k = 0; k < 2; ++k) dst[n][k] = *(const PG8_LAS bf16x8*)(lds + PG8_SB(b, h) + boff + n * 2048 + k * 1024); } while (0)
; #define PG8_MMA(ai, bj, At, Bt) do { __builtin_amdgcn_s_setprio(1); _Pragma("unroll") for (int m = 0; m < 4; ++m) _Pragma("unroll") for (int n = 0; n < 2; ++n) _Pragma("unroll") for (int k = 0; k < 2; ++k) \
;         acc[ai][bj][m][n] = __builtin_amdgcn_mfma_f32_16x16x32_bf16(Bt[n][k], At[m][k], acc[ai][bj][m][n], 0, 0, 0); __builtin_amdgcn_s_setprio(0); } while (0)
; #define PG8_WAIT_V(n) asm volatile("s_waitcnt vmcnt(" #n ")" ::: "memory")
; #define PG8_WAIT_L(n) asm volatile("s_waitcnt lgkmcnt(" #n ")" ::: "memory")
; template <class Epi, class Sched, bool ALIGN_EPI = false, bool SP2 = false>
; __device__ __forceinline__ void gemm_phase(PG8_LAS unsigned char* lds, const Gemm g, const Sched& S, const Epi& E) {
;     ...
;             const bool last = (t == nt - 2);
;             const char* a1 = cA + (size_t)(t + 1) * kstep;
;             const char* a2 = last ? nA : cA + (size_t)(t + 2) * kstep; const char* b2 = last ? nB : cB + (size_t)(t + 2) * kstep;
;             const char* a3 = a2 + kstep; const char* b3 = b2 + kstep;
;             if (last && has_next) S.a_ready(nxt);
;             if constexpr (SP2) {
;             PG8_LDB(B0, 0, 0); PG8_LDB(B1, 0, 1); PG8_SCHED; PG8_LDA(At, 0, 0); PG8_STAGE(PG8_SA(1, 1), a1 + hstep, voffA);
;             PG8_WAIT_V(8); PG8_WAIT_L(0); PG8_BAR; PG8_MMA(0, 0, At, B0); PG8_MMA(0, 1, At, B1); PG8_BAR; PG8_SCHED;
;             PG8_LDA(At, 0, 1); PG8_STAGE(PG8_SB(0, 0), b2, voffB); PG8_STAGE(PG8_SB(0, 1), b2 + hstep, voffB); PG8_STAGE(PG8_SA(0, 0), a2, voffA);
;             PG8_WAIT_V(8); PG8_WAIT_L(0); PG8_BAR; PG8_MMA(1, 0, At, B0); PG8_MMA(1, 1, At, B1); PG8_BAR; PG8_SCHED;
.LBB0_705:
	ds_read_b128 v[144:147], v151
	ds_read_b128 v[156:159], v151 offset:1024
	ds_read_b128 v[160:163], v151 offset:2048
	ds_read_b128 v[164:167], v151 offset:3072
	ds_read_b128 v[168:171], v152
	ds_read_b128 v[172:175], v152 offset:1024
	ds_read_b128 v[176:179], v152 offset:2048
	ds_read_b128 v[180:183], v152 offset:3072
	s_add_u32 s30, s28, 0xfff80080
	s_addc_u32 s31, s29, -1
	s_cmp_eq_u32 s60, 28
	s_cselect_b32 s35, s15, s31
	s_cselect_b32 s34, s56, s30
	s_cselect_b32 s31, s13, s59
	s_cselect_b32 s30, s57, s58
	v_lshl_add_u64 v[216:217], s[28:29], 0, v[136:137]
	s_add_i32 m0, s25, 0xc000
	ds_read_b128 v[184:187], v153
	ds_read_b128 v[188:191], v153 offset:1024
	ds_read_b128 v[192:195], v153 offset:2048
	ds_read_b128 v[196:199], v153 offset:3072
	ds_read_b128 v[200:203], v153 offset:4096
	ds_read_b128 v[204:207], v153 offset:5120
	ds_read_b128 v[208:211], v153 offset:6144
	ds_read_b128 v[212:215], v153 offset:7168
	global_load_lds_dwordx4 v[216:217], off
	v_lshl_add_u64 v[216:217], s[28:29], 0, v[138:139]
	s_add_i32 m0, s25, 0xe000
	s_nop 0
	global_load_lds_dwordx4 v[216:217], off
	s_mov_b32 m0, s48
	s_nop 0
	global_load_lds_dwordx4 v[250:251], off
	s_mov_b32 m0, s49
	s_nop 0
	global_load_lds_dwordx4 v[252:253], off
	s_waitcnt vmcnt(10)
	s_waitcnt lgkmcnt(0)
	s_barrier
	s_waitcnt lgkmcnt(0)
	v_mfma_f32_16x16x32_bf16 v[116:119], v[144:147], v[184:187], v[116:119]
	v_mfma_f32_16x16x32_bf16 v[112:115], v[160:163], v[184:187], v[112:115]
	s_add_u32 s62, s30, 0x80000
	v_mfma_f32_16x16x32_bf16 v[100:103], v[144:147], v[192:195], v[100:103]
	v_mfma_f32_16x16x32_bf16 v[96:99], v[160:163], v[192:195], v[96:99]
	s_addc_u32 s63, s31, 0
	v_mfma_f32_16x16x32_bf16 v[84:87], v[144:147], v[200:203], v[84:87]
	v_mfma_f32_16x16x32_bf16 v[80:83], v[160:163], v[200:203], v[80:83]
	v_lshl_add_u64 v[216:217], s[30:31], 0, v[132:133]
	v_mfma_f32_16x16x32_bf16 v[72:75], v[144:147], v[208:211], v[72:75]
	v_mfma_f32_16x16x32_bf16 v[68:71], v[160:163], v[208:211], v[68:71]
	v_lshl_add_u64 v[218:219], s[30:31], 0, v[128:129]
	v_mfma_f32_16x16x32_bf16 v[116:119], v[156:159], v[188:191], v[116:119]
	v_mfma_f32_16x16x32_bf16 v[112:115], v[164:167], v[188:191], v[112:115]
	v_lshl_add_u64 v[246:247], s[62:63], 0, v[132:133]
	v_mfma_f32_16x16x32_bf16 v[100:103], v[156:159], v[196:199], v[100:103]
	v_mfma_f32_16x16x32_bf16 v[96:99], v[164:167], v[196:199], v[96:99]
	v_lshl_add_u64 v[222:223], s[34:35], 0, v[130:131]
	v_mfma_f32_16x16x32_bf16 v[84:87], v[156:159], v[204:207], v[84:87]
	v_mfma_f32_16x16x32_bf16 v[80:83], v[164:167], v[204:207], v[80:83]
	v_lshl_add_u64 v[248:249], s[62:63], 0, v[128:129]
	v_mfma_f32_16x16x32_bf16 v[72:75], v[156:159], v[212:215], v[72:75]
	v_mfma_f32_16x16x32_bf16 v[68:71], v[164:167], v[212:215], v[68:71]
	v_lshl_add_u64 v[220:221], s[34:35], 0, v[134:135]
	v_mfma_f32_16x16x32_bf16 v[124:127], v[168:171], v[184:187], v[124:127]
	v_mfma_f32_16x16x32_bf16 v[120:123], v[176:179], v[184:187], v[120:123]
	v_mfma_f32_16x16x32_bf16 v[108:111], v[168:171], v[192:195], v[108:111]
	v_mfma_f32_16x16x32_bf16 v[104:107], v[176:179], v[192:195], v[104:107]
	v_mfma_f32_16x16x32_bf16 v[92:95], v[168:171], v[200:203], v[92:95]
	v_mfma_f32_16x16x32_bf16 v[88:91], v[176:179], v[200:203], v[88:91]
	v_mfma_f32_16x16x32_bf16 v[76:79], v[168:171], v[208:211], v[76:79]
	v_mfma_f32_16x16x32_bf16 v[64:67], v[176:179], v[208:211], v[64:67]
	v_mfma_f32_16x16x32_bf16 v[124:127], v[172:175], v[188:191], v[124:127]
	v_mfma_f32_16x16x32_bf16 v[120:123], v[180:183], v[188:191], v[120:123]
	v_mfma_f32_16x16x32_bf16 v[108:111], v[172:175], v[196:199], v[108:111]
	v_mfma_f32_16x16x32_bf16 v[104:107], v[180:183], v[196:199], v[104:107]
	v_mfma_f32_16x16x32_bf16 v[92:95], v[172:175], v[204:207], v[92:95]
	v_mfma_f32_16x16x32_bf16 v[88:91], v[180:183], v[204:207], v[88:91]
	v_mfma_f32_16x16x32_bf16 v[76:79], v[172:175], v[212:215], v[76:79]
	v_mfma_f32_16x16x32_bf16 v[64:67], v[180:183], v[212:215], v[64:67]
	s_add_i32 s61, s52, s42
	s_mov_b32 m0, s61
	s_barrier
	global_load_lds_dwordx4 v[216:217], off
	s_add_i32 m0, s61, 0x2000
	s_add_i32 s61, s53, s42
	global_load_lds_dwordx4 v[218:219], off
	s_mov_b32 m0, s61
	s_nop 0
	global_load_lds_dwordx4 v[246:247], off
	s_add_i32 m0, s61, 0x2000
	s_nop 0
	global_load_lds_dwordx4 v[248:249], off
	ds_read_b128 v[184:187], v153 offset:16384
	ds_read_b128 v[188:191], v153 offset:17408
	ds_read_b128 v[192:195], v153 offset:18432
	ds_read_b128 v[196:199], v153 offset:19456
	ds_read_b128 v[200:203], v153 offset:20480
	ds_read_b128 v[204:207], v153 offset:21504
	ds_read_b128 v[208:211], v153 offset:22528
	ds_read_b128 v[212:215], v153 offset:23552
	s_waitcnt vmcnt(4)
	s_waitcnt lgkmcnt(0)
	s_barrier
; #define PG8_STAGE(bufoff, gbase, voff) do { _Pragma("unroll") for (int _i = 0; _i < 2; ++_i) \
;         __builtin_amdgcn_global_load_lds((const unsigned*)((const char*)(gbase) + (voff)[_i]), (PG8_LAS unsigned*)(lds + (bufoff) + ldsw + _i * 8192), 16, 0, 0); } while (0)
; #define PG8_LDA(dst, b, h) do { _Pragma("unroll") for (int m = 0; m < 4; ++m) _Pragma("unroll") for (int k = 0; k < 2; ++k) dst[m][k] = *(const PG8_LAS bf16x8*)(lds + PG8_SA(b, h) + aoff + m * 2048 + k * 1024); } while (0)
; #define PG8_LDB(dst, b, h) do { _Pragma("unroll") for (int n = 0; n < 2; ++n) _Pragma("unroll") for (int k = 0; k < 2; ++k) dst[n][k] = *(const PG8_LAS bf16x8*)(lds + PG8_SB(b, h) + boff + n * 2048 + k * 1024); } while (0)
; #define PG8_MMA(ai, bj, At, Bt) do { __builtin_amdgcn_s_setprio(1); _Pragma("unroll") for (int m = 0; m < 4; ++m) _Pragma("unroll") for (int n = 0; n < 2; ++n) _Pragma("unroll") for (int k = 0; k < 2; ++k) \
;         acc[ai][bj][m][n] = __builtin_amdgcn_mfma_f32_16x16x32_bf16(Bt[n][k], At[m][k], acc[ai][bj][m][n], 0, 0, 0); __builtin_amdgcn_s_setprio(0); } while (0)
; #define PG8_WAIT_V(n) asm volatile("s_waitcnt vmcnt(" #n ")" ::: "memory")
; #define PG8_WAIT_L(n) asm volatile("s_waitcnt lgkmcnt(" #n ")" ::: "memory")
; #define PG8_BAR __builtin_amdgcn_s_barrier()
; #define PG8_SCHED __builtin_amdgcn_sched_barrier(0)
; template <class Epi, class Sched, bool ALIGN_EPI = false, bool SP2 = false>
; __device__ __forceinline__ void gemm_phase(PG8_LAS unsigned char* lds, const Gemm g, const Sched& S, const Epi& E) {
;     ...
;             PG8_WAIT_V(8); PG8_WAIT_L(0); PG8_BAR; PG8_MMA(1, 0, At, B0); PG8_MMA(1, 1, At, B1); PG8_BAR; PG8_SCHED;
;             PG8_LDB(B0, 1, 0); PG8_LDB(B1, 1, 1); PG8_SCHED; PG8_LDA(At, 1, 0); PG8_STAGE(PG8_SA(0, 1), a2 + hstep, voffA);
;             PG8_WAIT_V(8); PG8_WAIT_L(0); PG8_BAR; PG8_MMA(0, 0, At, B0); PG8_MMA(0, 1, At, B1); PG8_BAR; PG8_SCHED;
	s_waitcnt lgkmcnt(0)
	v_mfma_f32_16x16x32_bf16 v[56:59], v[144:147], v[184:187], v[56:59]
	v_mfma_f32_16x16x32_bf16 v[52:55], v[160:163], v[184:187], v[52:55]
	v_mfma_f32_16x16x32_bf16 v[40:43], v[144:147], v[192:195], v[40:43]
	v_mfma_f32_16x16x32_bf16 v[36:39], v[160:163], v[192:195], v[36:39]
	v_mfma_f32_16x16x32_bf16 v[24:27], v[144:147], v[200:203], v[24:27]
	v_mfma_f32_16x16x32_bf16 v[20:23], v[160:163], v[200:203], v[20:23]
	v_mfma_f32_16x16x32_bf16 v[8:11], v[144:147], v[208:211], v[8:11]
	v_mfma_f32_16x16x32_bf16 v[0:3], v[160:163], v[208:211], v[0:3]
	v_mfma_f32_16x16x32_bf16 v[56:59], v[156:159], v[188:191], v[56:59]
	v_mfma_f32_16x16x32_bf16 v[52:55], v[164:167], v[188:191], v[52:55]
	v_mfma_f32_16x16x32_bf16 v[40:43], v[156:159], v[196:199], v[40:43]
	v_mfma_f32_16x16x32_bf16 v[36:39], v[164:167], v[196:199], v[36:39]
	v_mfma_f32_16x16x32_bf16 v[24:27], v[156:159], v[204:207], v[24:27]
	v_mfma_f32_16x16x32_bf16 v[20:23], v[164:167], v[204:207], v[20:23]
	v_mfma_f32_16x16x32_bf16 v[8:11], v[156:159], v[212:215], v[8:11]
	v_mfma_f32_16x16x32_bf16 v[0:3], v[164:167], v[212:215], v[0:3]
	v_mfma_f32_16x16x32_bf16 v[60:63], v[168:171], v[184:187], v[60:63]
	v_mfma_f32_16x16x32_bf16 v[48:51], v[176:179], v[184:187], v[48:51]
	v_mfma_f32_16x16x32_bf16 v[44:47], v[168:171], v[192:195], v[44:47]
	v_mfma_f32_16x16x32_bf16 v[32:35], v[176:179], v[192:195], v[32:35]
	v_mfma_f32_16x16x32_bf16 v[28:31], v[168:171], v[200:203], v[28:31]
	v_mfma_f32_16x16x32_bf16 v[16:19], v[176:179], v[200:203], v[16:19]
	v_mfma_f32_16x16x32_bf16 v[12:15], v[168:171], v[208:211], v[12:15]
	v_mfma_f32_16x16x32_bf16 v[4:7], v[176:179], v[208:211], v[4:7]
	v_mfma_f32_16x16x32_bf16 v[60:63], v[172:175], v[188:191], v[60:63]
	v_mfma_f32_16x16x32_bf16 v[48:51], v[180:183], v[188:191], v[48:51]
	v_mfma_f32_16x16x32_bf16 v[44:47], v[172:175], v[196:199], v[44:47]
	v_mfma_f32_16x16x32_bf16 v[32:35], v[180:183], v[196:199], v[32:35]
	v_mfma_f32_16x16x32_bf16 v[28:31], v[172:175], v[204:207], v[28:31]
	v_mfma_f32_16x16x32_bf16 v[16:19], v[180:183], v[204:207], v[16:19]
	v_mfma_f32_16x16x32_bf16 v[12:15], v[172:175], v[212:215], v[12:15]
	v_mfma_f32_16x16x32_bf16 v[4:7], v[180:183], v[212:215], v[4:7]
	s_barrier
	s_add_i32 s61, 0, 0x18000
	v_add_u32_e32 v155, s61, v149
	s_add_i32 s62, 0, 0x1c000
	ds_read_b128 v[144:147], v155
	ds_read_b128 v[156:159], v155 offset:1024
	ds_read_b128 v[160:163], v155 offset:2048
	ds_read_b128 v[164:167], v155 offset:3072
	v_add_u32_e32 v155, s62, v149
	ds_read_b128 v[168:171], v155
	ds_read_b128 v[172:175], v155 offset:1024
	ds_read_b128 v[176:179], v155 offset:2048
	ds_read_b128 v[180:183], v155 offset:3072
	s_add_u32 s34, s34, 0x80000
	s_addc_u32 s35, s35, 0
	s_mov_b32 m0, s46
	v_lshl_add_u64 v[224:225], s[34:35], 0, v[134:135]
	ds_read_b128 v[184:187], v153 offset:32768
	ds_read_b128 v[188:191], v153 offset:33792
	ds_read_b128 v[192:195], v153 offset:34816
	ds_read_b128 v[196:199], v153 offset:35840
	ds_read_b128 v[200:203], v153 offset:36864
	ds_read_b128 v[204:207], v153 offset:37888
	ds_read_b128 v[208:211], v153 offset:38912
	ds_read_b128 v[212:215], v153 offset:39936
	global_load_lds_dwordx4 v[224:225], off
	v_lshl_add_u64 v[224:225], s[34:35], 0, v[130:131]
	s_mov_b32 m0, s47
	s_nop 0
	global_load_lds_dwordx4 v[224:225], off
	s_mov_b32 m0, s25
	s_nop 0
	global_load_lds_dwordx4 v[220:221], off
	s_mov_b32 m0, s45
	s_nop 0
	global_load_lds_dwordx4 v[222:223], off
	s_waitcnt vmcnt(10)
	s_waitcnt lgkmcnt(0)
	s_barrier
; #define PG8_STAGE(bufoff, gbase, voff) do { _Pragma("unroll") for (int _i = 0; _i < 2; ++_i) \
;         __builtin_amdgcn_global_load_lds((const unsigned*)((const char*)(gbase) + (voff)[_i]), (PG8_LAS unsigned*)(lds + (bufoff) + ldsw + _i * 8192), 16, 0, 0); } while (0)
; #define PG8_LDA(dst, b, h) do { _Pragma("unroll") for (int m = 0; m < 4; ++m) _Pragma("unroll") for (int k = 0; k < 2; ++k) dst[m][k] = *(const PG8_LAS bf16x8*)(lds + PG8_SA(b, h) + aoff + m * 2048 + k * 1024); } while (0)
; #define PG8_MMA(ai, bj, At, Bt) do { __builtin_amdgcn_s_setprio(1); _Pragma("unroll") for (int m = 0; m < 4; ++m) _Pragma("unroll") for (int n = 0; n < 2; ++n) _Pragma("unroll") for (int k = 0; k < 2; ++k) \
;         acc[ai][bj][m][n] = __builtin_amdgcn_mfma_f32_16x16x32_bf16(Bt[n][k], At[m][k], acc[ai][bj][m][n], 0, 0, 0); __builtin_amdgcn_s_setprio(0); } while (0)
; #define PG8_WAIT_V(n) asm volatile("s_waitcnt vmcnt(" #n ")" ::: "memory")
; #define PG8_WAIT_L(n) asm volatile("s_waitcnt lgkmcnt(" #n ")" ::: "memory")
; #define PG8_BAR __builtin_amdgcn_s_barrier()
; #define PG8_SCHED __builtin_amdgcn_sched_barrier(0)
; template <class Epi, class Sched, bool ALIGN_EPI = false, bool SP2 = false>
; __device__ __forceinline__ void gemm_phase(PG8_LAS unsigned char* lds, const Gemm g, const Sched& S, const Epi& E) {
;     ...
;             PG8_WAIT_V(8); PG8_WAIT_L(0); PG8_BAR; PG8_MMA(0, 0, At, B0); PG8_MMA(0, 1, At, B1); PG8_BAR; PG8_SCHED;
;             PG8_LDA(At, 1, 1); PG8_STAGE(PG8_SB(1, 0), b3, voffB); PG8_STAGE(PG8_SB(1, 1), b3 + hstep, voffB); PG8_STAGE(PG8_SA(1, 0), a3, voffA);
;             PG8_WAIT_V(8); PG8_WAIT_L(0); PG8_BAR; PG8_MMA(1, 0, At, B0); PG8_MMA(1, 1, At, B1); PG8_BAR; PG8_SCHED;
	s_waitcnt lgkmcnt(0)
	v_mfma_f32_16x16x32_bf16 v[116:119], v[144:147], v[184:187], v[116:119]
	v_mfma_f32_16x16x32_bf16 v[112:115], v[160:163], v[184:187], v[112:115]
	s_add_u32 s30, s30, 0x80080
	v_mfma_f32_16x16x32_bf16 v[100:103], v[144:147], v[192:195], v[100:103]
	v_mfma_f32_16x16x32_bf16 v[96:99], v[160:163], v[192:195], v[96:99]
	s_addc_u32 s31, s31, 0
	v_mfma_f32_16x16x32_bf16 v[84:87], v[144:147], v[200:203], v[84:87]
	v_mfma_f32_16x16x32_bf16 v[80:83], v[160:163], v[200:203], v[80:83]
	v_lshl_add_u64 v[216:217], v[216:217], 0, s[8:9]
	v_mfma_f32_16x16x32_bf16 v[72:75], v[144:147], v[208:211], v[72:75]
	v_mfma_f32_16x16x32_bf16 v[68:71], v[160:163], v[208:211], v[68:71]
	v_lshl_add_u64 v[218:219], v[218:219], 0, s[8:9]
	v_mfma_f32_16x16x32_bf16 v[116:119], v[156:159], v[188:191], v[116:119]
	v_mfma_f32_16x16x32_bf16 v[112:115], v[164:167], v[188:191], v[112:115]
	v_lshl_add_u64 v[246:247], s[30:31], 0, v[132:133]
	v_mfma_f32_16x16x32_bf16 v[100:103], v[156:159], v[196:199], v[100:103]
	v_mfma_f32_16x16x32_bf16 v[96:99], v[164:167], v[196:199], v[96:99]
	v_lshl_add_u64 v[248:249], s[30:31], 0, v[128:129]
	v_mfma_f32_16x16x32_bf16 v[84:87], v[156:159], v[204:207], v[84:87]
	v_mfma_f32_16x16x32_bf16 v[80:83], v[164:167], v[204:207], v[80:83]
	v_lshl_add_u64 v[250:251], v[220:221], 0, s[8:9]
	v_mfma_f32_16x16x32_bf16 v[72:75], v[156:159], v[212:215], v[72:75]
	v_mfma_f32_16x16x32_bf16 v[68:71], v[164:167], v[212:215], v[68:71]
	v_lshl_add_u64 v[252:253], v[222:223], 0, s[8:9]
	v_mfma_f32_16x16x32_bf16 v[124:127], v[168:171], v[184:187], v[124:127]
	v_mfma_f32_16x16x32_bf16 v[120:123], v[176:179], v[184:187], v[120:123]
	v_mfma_f32_16x16x32_bf16 v[108:111], v[168:171], v[192:195], v[108:111]
	v_mfma_f32_16x16x32_bf16 v[104:107], v[176:179], v[192:195], v[104:107]
	v_mfma_f32_16x16x32_bf16 v[92:95], v[168:171], v[200:203], v[92:95]
	v_mfma_f32_16x16x32_bf16 v[88:91], v[176:179], v[200:203], v[88:91]
	v_mfma_f32_16x16x32_bf16 v[76:79], v[168:171], v[208:211], v[76:79]
	v_mfma_f32_16x16x32_bf16 v[64:67], v[176:179], v[208:211], v[64:67]
	v_mfma_f32_16x16x32_bf16 v[124:127], v[172:175], v[188:191], v[124:127]
	v_mfma_f32_16x16x32_bf16 v[120:123], v[180:183], v[188:191], v[120:123]
	v_mfma_f32_16x16x32_bf16 v[108:111], v[172:175], v[196:199], v[108:111]
	v_mfma_f32_16x16x32_bf16 v[104:107], v[180:183], v[196:199], v[104:107]
	v_mfma_f32_16x16x32_bf16 v[92:95], v[172:175], v[204:207], v[92:95]
	v_mfma_f32_16x16x32_bf16 v[88:91], v[180:183], v[204:207], v[88:91]
	v_mfma_f32_16x16x32_bf16 v[76:79], v[172:175], v[212:215], v[76:79]
	v_mfma_f32_16x16x32_bf16 v[64:67], v[180:183], v[212:215], v[64:67]
	s_add_i32 s34, s61, s42
	s_mov_b32 m0, s34
	s_barrier
	global_load_lds_dwordx4 v[216:217], off
	s_add_i32 m0, s34, 0x2000
	s_add_i32 s34, s62, s42
	global_load_lds_dwordx4 v[218:219], off
	s_mov_b32 m0, s34
	s_nop 0
	global_load_lds_dwordx4 v[246:247], off
	s_add_i32 m0, s34, 0x2000
	s_nop 0
	global_load_lds_dwordx4 v[248:249], off
	ds_read_b128 v[184:187], v153 offset:49152
	ds_read_b128 v[188:191], v153 offset:50176
	ds_read_b128 v[192:195], v153 offset:51200
	ds_read_b128 v[196:199], v153 offset:52224
	ds_read_b128 v[200:203], v153 offset:53248
	ds_read_b128 v[204:207], v153 offset:54272
	ds_read_b128 v[208:211], v153 offset:55296
	ds_read_b128 v[212:215], v153 offset:56320
	s_waitcnt vmcnt(4)
	s_waitcnt lgkmcnt(0)
	s_barrier
	s_waitcnt lgkmcnt(0)
	v_mfma_f32_16x16x32_bf16 v[56:59], v[144:147], v[184:187], v[56:59]
	v_mfma_f32_16x16x32_bf16 v[52:55], v[160:163], v[184:187], v[52:55]
	v_mfma_f32_16x16x32_bf16 v[40:43], v[144:147], v[192:195], v[40:43]
	v_mfma_f32_16x16x32_bf16 v[36:39], v[160:163], v[192:195], v[36:39]
	v_mfma_f32_16x16x32_bf16 v[24:27], v[144:147], v[200:203], v[24:27]
	v_mfma_f32_16x16x32_bf16 v[20:23], v[160:163], v[200:203], v[20:23]
	v_mfma_f32_16x16x32_bf16 v[8:11], v[144:147], v[208:211], v[8:11]
	v_mfma_f32_16x16x32_bf16 v[0:3], v[160:163], v[208:211], v[0:3]
	v_mfma_f32_16x16x32_bf16 v[56:59], v[156:159], v[188:191], v[56:59]
	v_mfma_f32_16x16x32_bf16 v[52:55], v[164:167], v[188:191], v[52:55]
	v_mfma_f32_16x16x32_bf16 v[40:43], v[156:159], v[196:199], v[40:43]
	v_mfma_f32_16x16x32_bf16 v[36:39], v[164:167], v[196:199], v[36:39]
	v_mfma_f32_16x16x32_bf16 v[24:27], v[156:159], v[204:207], v[24:27]
	v_mfma_f32_16x16x32_bf16 v[20:23], v[164:167], v[204:207], v[20:23]
	v_mfma_f32_16x16x32_bf16 v[8:11], v[156:159], v[212:215], v[8:11]
	v_mfma_f32_16x16x32_bf16 v[0:3], v[164:167], v[212:215], v[0:3]
	v_mfma_f32_16x16x32_bf16 v[60:63], v[168:171], v[184:187], v[60:63]
	v_mfma_f32_16x16x32_bf16 v[48:51], v[176:179], v[184:187], v[48:51]
	v_mfma_f32_16x16x32_bf16 v[44:47], v[168:171], v[192:195], v[44:47]
	v_mfma_f32_16x16x32_bf16 v[32:35], v[176:179], v[192:195], v[32:35]
	s_add_i32 s60, s60, 2
	v_mfma_f32_16x16x32_bf16 v[28:31], v[168:171], v[200:203], v[28:31]
	v_mfma_f32_16x16x32_bf16 v[16:19], v[176:179], v[200:203], v[16:19]
	s_add_u32 s28, s28, 0x100
	v_mfma_f32_16x16x32_bf16 v[12:15], v[168:171], v[208:211], v[12:15]
	v_mfma_f32_16x16x32_bf16 v[4:7], v[176:179], v[208:211], v[4:7]
	s_addc_u32 s29, s29, 0
	v_mfma_f32_16x16x32_bf16 v[60:63], v[172:175], v[188:191], v[60:63]
	v_mfma_f32_16x16x32_bf16 v[48:51], v[180:183], v[188:191], v[48:51]
	s_add_u32 s58, s58, 0x100
	v_mfma_f32_16x16x32_bf16 v[44:47], v[172:175], v[196:199], v[44:47]
	v_mfma_f32_16x16x32_bf16 v[32:35], v[180:183], v[196:199], v[32:35]
	s_addc_u32 s59, s59, 0
	v_mfma_f32_16x16x32_bf16 v[28:31], v[172:175], v[204:207], v[28:31]
	v_mfma_f32_16x16x32_bf16 v[16:19], v[180:183], v[204:207], v[16:19]
	v_mfma_f32_16x16x32_bf16 v[12:15], v[172:175], v[212:215], v[12:15]
	v_mfma_f32_16x16x32_bf16 v[4:7], v[180:183], v[212:215], v[4:7]
	s_barrier
	s_cmp_gt_u32 s60, 29
	s_cbranch_scc0 .LBB0_705
	s_and_b64 vcc, exec, s[10:11]
	s_cbranch_vccz .LBB0_708
	s_barrier

; #define PG8_STAGE(bufoff, gbase, voff) do { _Pragma("unroll") for (int _i = 0; _i < 2; ++_i) \
;         __builtin_amdgcn_global_load_lds((const unsigned*)((const char*)(gbase) + (voff)[_i]), (PG8_LAS unsigned*)(lds + (bufoff) + ldsw + _i * 8192), 16, 0, 0); } while (0)
; #define PG8_LDA(dst, b, h) do { _Pragma("unroll") for (int m = 0; m < 4; ++m) _Pragma("unroll") for (int k = 0; k < 2; ++k) dst[m][k] = *(const PG8_LAS bf16x8*)(lds + PG8_SA(b, h) + aoff + m * 2048 + k * 1024); } while (0)
; #define PG8_LDB(dst, b, h) do { _Pragma("unroll") for (int n = 0; n < 2; ++n) _Pragma("unroll") for (int k = 0; k < 2; ++k) dst[n][k] = *(const PG8_LAS bf16x8*)(lds + PG8_SB(b, h) + boff + n * 2048 + k * 1024); } while (0)
; #define PG8_MMA(ai, bj, At, Bt) do { __builtin_amdgcn_s_setprio(1); _Pragma("unroll") for (int m = 0; m < 4; ++m) _Pragma("unroll") for (int n = 0; n < 2; ++n) _Pragma("unroll") for (int k = 0; k < 2; ++k) \
;         acc[ai][bj][m][n] = __builtin_amdgcn_mfma_f32_16x16x32_bf16(Bt[n][k], At[m][k], acc[ai][bj][m][n], 0, 0, 0); __builtin_amdgcn_s_setprio(0); } while (0)
; #define PG8_WAIT_V(n) asm volatile("s_waitcnt vmcnt(" #n ")" ::: "memory")
; #define PG8_WAIT_L(n) asm volatile("s_waitcnt lgkmcnt(" #n ")" ::: "memory")
; template <class Epi, class Sched, bool ALIGN_EPI = false, bool SP2 = false>
; __device__ __forceinline__ void gemm_phase(PG8_LAS unsigned char* lds, const Gemm g, const Sched& S, const Epi& E) {
;     ...
;             const bool last = (t == nt - 2);
;             const char* a1 = cA + (size_t)(t + 1) * kstep;
;             const char* a2 = last ? nA : cA + (size_t)(t + 2) * kstep; const char* b2 = last ? nB : cB + (size_t)(t + 2) * kstep;
;             const char* a3 = a2 + kstep; const char* b3 = b2 + kstep;
;             if (last && has_next) S.a_ready(nxt);
;             if constexpr (SP2) {
;             PG8_LDB(B0, 0, 0); PG8_LDB(B1, 0, 1); PG8_SCHED; PG8_LDA(At, 0, 0); PG8_STAGE(PG8_SA(1, 1), a1 + hstep, voffA);
;             PG8_WAIT_V(8); PG8_WAIT_L(0); PG8_BAR; PG8_MMA(0, 0, At, B0); PG8_MMA(0, 1, At, B1); PG8_BAR; PG8_SCHED;
;             PG8_LDA(At, 0, 1); PG8_STAGE(PG8_SB(0, 0), b2, voffB); PG8_STAGE(PG8_SB(0, 1), b2 + hstep, voffB); PG8_STAGE(PG8_SA(0, 0), a2, voffA);
;             PG8_WAIT_V(8); PG8_WAIT_L(0); PG8_BAR; PG8_MMA(1, 0, At, B0); PG8_MMA(1, 1, At, B1); PG8_BAR; PG8_SCHED;
.LBB0_788:
	ds_read_b128 v[128:131], v189
	ds_read_b128 v[132:135], v189 offset:1024
	ds_read_b128 v[136:139], v189 offset:2048
	ds_read_b128 v[140:143], v189 offset:3072
	ds_read_b128 v[144:147], v190
	ds_read_b128 v[148:151], v190 offset:1024
	ds_read_b128 v[168:171], v190 offset:2048
	ds_read_b128 v[172:175], v190 offset:3072
	s_add_u32 s24, s22, 0x100
	s_addc_u32 s25, s23, 0
	s_cmpk_eq_i32 s58, 0x54
	s_cselect_b32 s31, s7, s25
	s_cselect_b32 s30, s6, s24
	s_cselect_b32 s29, s17, s57
	s_cselect_b32 s28, s16, s56
	v_lshl_add_u64 v[184:185], s[22:23], 0, v[160:161]
	s_add_i32 m0, s40, 0xc000
	ds_read_b128 v[176:179], v191
	ds_read_b128 v[180:183], v191 offset:1024
	ds_read_b128 v[192:195], v191 offset:2048
	ds_read_b128 v[196:199], v191 offset:3072
	ds_read_b128 v[200:203], v191 offset:4096
	ds_read_b128 v[204:207], v191 offset:5120
	ds_read_b128 v[208:211], v191 offset:6144
	ds_read_b128 v[212:215], v191 offset:7168
	global_load_lds_dwordx4 v[184:185], off
	v_lshl_add_u64 v[184:185], s[22:23], 0, v[162:163]
	s_add_i32 m0, s40, 0xe000
	s_nop 0
	global_load_lds_dwordx4 v[184:185], off
	s_mov_b32 m0, s45
	s_nop 0
	global_load_lds_dwordx4 v[250:251], off
	s_mov_b32 m0, s46
	s_nop 0
	global_load_lds_dwordx4 v[252:253], off
	s_waitcnt vmcnt(10)
	s_waitcnt lgkmcnt(0)
	s_barrier
	s_waitcnt lgkmcnt(0)
	v_mfma_f32_16x16x32_bf16 v[124:127], v[128:131], v[176:179], v[124:127]
	v_mfma_f32_16x16x32_bf16 v[120:123], v[136:139], v[176:179], v[120:123]
	s_add_u32 s22, s28, 0x160000
	v_mfma_f32_16x16x32_bf16 v[108:111], v[128:131], v[192:195], v[108:111]
	v_mfma_f32_16x16x32_bf16 v[104:107], v[136:139], v[192:195], v[104:107]
	s_addc_u32 s23, s29, 0
	v_mfma_f32_16x16x32_bf16 v[92:95], v[128:131], v[200:203], v[92:95]
	v_mfma_f32_16x16x32_bf16 v[88:91], v[136:139], v[200:203], v[88:91]
	v_lshl_add_u64 v[184:185], s[28:29], 0, v[154:155]
	v_mfma_f32_16x16x32_bf16 v[76:79], v[128:131], v[208:211], v[76:79]
	v_mfma_f32_16x16x32_bf16 v[72:75], v[136:139], v[208:211], v[72:75]
	v_lshl_add_u64 v[216:217], s[28:29], 0, v[158:159]
	v_mfma_f32_16x16x32_bf16 v[124:127], v[132:135], v[180:183], v[124:127]
	v_mfma_f32_16x16x32_bf16 v[120:123], v[140:143], v[180:183], v[120:123]
	v_lshl_add_u64 v[246:247], s[22:23], 0, v[154:155]
	v_mfma_f32_16x16x32_bf16 v[108:111], v[132:135], v[196:199], v[108:111]
	v_mfma_f32_16x16x32_bf16 v[104:107], v[140:143], v[196:199], v[104:107]
	v_lshl_add_u64 v[220:221], s[30:31], 0, v[156:157]
	v_mfma_f32_16x16x32_bf16 v[92:95], v[132:135], v[204:207], v[92:95]
	v_mfma_f32_16x16x32_bf16 v[88:91], v[140:143], v[204:207], v[88:91]
	v_lshl_add_u64 v[248:249], s[22:23], 0, v[158:159]
	v_mfma_f32_16x16x32_bf16 v[76:79], v[132:135], v[212:215], v[76:79]
	v_mfma_f32_16x16x32_bf16 v[72:75], v[140:143], v[212:215], v[72:75]
	v_lshl_add_u64 v[218:219], s[30:31], 0, v[152:153]
	v_mfma_f32_16x16x32_bf16 v[116:119], v[144:147], v[176:179], v[116:119]
	v_mfma_f32_16x16x32_bf16 v[112:115], v[168:171], v[176:179], v[112:115]
	v_mfma_f32_16x16x32_bf16 v[100:103], v[144:147], v[192:195], v[100:103]
	v_mfma_f32_16x16x32_bf16 v[96:99], v[168:171], v[192:195], v[96:99]
	v_mfma_f32_16x16x32_bf16 v[84:87], v[144:147], v[200:203], v[84:87]
	v_mfma_f32_16x16x32_bf16 v[80:83], v[168:171], v[200:203], v[80:83]
	v_mfma_f32_16x16x32_bf16 v[68:71], v[144:147], v[208:211], v[68:71]
	v_mfma_f32_16x16x32_bf16 v[64:67], v[168:171], v[208:211], v[64:67]
	v_mfma_f32_16x16x32_bf16 v[116:119], v[148:151], v[180:183], v[116:119]
	v_mfma_f32_16x16x32_bf16 v[112:115], v[172:175], v[180:183], v[112:115]
	v_mfma_f32_16x16x32_bf16 v[100:103], v[148:151], v[196:199], v[100:103]
	v_mfma_f32_16x16x32_bf16 v[96:99], v[172:175], v[196:199], v[96:99]
	v_mfma_f32_16x16x32_bf16 v[84:87], v[148:151], v[204:207], v[84:87]
	v_mfma_f32_16x16x32_bf16 v[80:83], v[172:175], v[204:207], v[80:83]
	v_mfma_f32_16x16x32_bf16 v[68:71], v[148:151], v[212:215], v[68:71]
	v_mfma_f32_16x16x32_bf16 v[64:67], v[172:175], v[212:215], v[64:67]
	s_add_i32 s22, s49, s39
	s_mov_b32 m0, s22
	s_barrier
	global_load_lds_dwordx4 v[184:185], off
	s_add_i32 m0, s22, 0x2000
	s_add_i32 s59, s50, s39
	global_load_lds_dwordx4 v[216:217], off
	s_mov_b32 m0, s59
	s_nop 0
	global_load_lds_dwordx4 v[246:247], off
	s_add_i32 m0, s59, 0x2000
	s_nop 0
	global_load_lds_dwordx4 v[248:249], off
	ds_read_b128 v[176:179], v191 offset:16384
	ds_read_b128 v[180:183], v191 offset:17408
	ds_read_b128 v[192:195], v191 offset:18432
	ds_read_b128 v[196:199], v191 offset:19456
	ds_read_b128 v[200:203], v191 offset:20480
	ds_read_b128 v[204:207], v191 offset:21504
	ds_read_b128 v[208:211], v191 offset:22528
	ds_read_b128 v[212:215], v191 offset:23552
	s_waitcnt vmcnt(4)
	s_waitcnt lgkmcnt(0)
	s_barrier
; #define PG8_STAGE(bufoff, gbase, voff) do { _Pragma("unroll") for (int _i = 0; _i < 2; ++_i) \
;         __builtin_amdgcn_global_load_lds((const unsigned*)((const char*)(gbase) + (voff)[_i]), (PG8_LAS unsigned*)(lds + (bufoff) + ldsw + _i * 8192), 16, 0, 0); } while (0)
; #define PG8_LDA(dst, b, h) do { _Pragma("unroll") for (int m = 0; m < 4; ++m) _Pragma("unroll") for (int k = 0; k < 2; ++k) dst[m][k] = *(const PG8_LAS bf16x8*)(lds + PG8_SA(b, h) + aoff + m * 2048 + k * 1024); } while (0)
; #define PG8_LDB(dst, b, h) do { _Pragma("unroll") for (int n = 0; n < 2; ++n) _Pragma("unroll") for (int k = 0; k < 2; ++k) dst[n][k] = *(const PG8_LAS bf16x8*)(lds + PG8_SB(b, h) + boff + n * 2048 + k * 1024); } while (0)
; #define PG8_MMA(ai, bj, At, Bt) do { __builtin_amdgcn_s_setprio(1); _Pragma("unroll") for (int m = 0; m < 4; ++m) _Pragma("unroll") for (int n = 0; n < 2; ++n) _Pragma("unroll") for (int k = 0; k < 2; ++k) \
;         acc[ai][bj][m][n] = __builtin_amdgcn_mfma_f32_16x16x32_bf16(Bt[n][k], At[m][k], acc[ai][bj][m][n], 0, 0, 0); __builtin_amdgcn_s_setprio(0); } while (0)
; #define PG8_WAIT_V(n) asm volatile("s_waitcnt vmcnt(" #n ")" ::: "memory")
; #define PG8_WAIT_L(n) asm volatile("s_waitcnt lgkmcnt(" #n ")" ::: "memory")
; #define PG8_BAR __builtin_amdgcn_s_barrier()
; #define PG8_SCHED __builtin_amdgcn_sched_barrier(0)
; template <class Epi, class Sched, bool ALIGN_EPI = false, bool SP2 = false>
; __device__ __forceinline__ void gemm_phase(PG8_LAS unsigned char* lds, const Gemm g, const Sched& S, const Epi& E) {
;     ...
;             PG8_WAIT_V(8); PG8_WAIT_L(0); PG8_BAR; PG8_MMA(1, 0, At, B0); PG8_MMA(1, 1, At, B1); PG8_BAR; PG8_SCHED;
;             PG8_LDB(B0, 1, 0); PG8_LDB(B1, 1, 1); PG8_SCHED; PG8_LDA(At, 1, 0); PG8_STAGE(PG8_SA(0, 1), a2 + hstep, voffA);
;             PG8_WAIT_V(8); PG8_WAIT_L(0); PG8_BAR; PG8_MMA(0, 0, At, B0); PG8_MMA(0, 1, At, B1); PG8_BAR; PG8_SCHED;
	s_waitcnt lgkmcnt(0)
	v_mfma_f32_16x16x32_bf16 v[60:63], v[128:131], v[176:179], v[60:63]
	v_mfma_f32_16x16x32_bf16 v[56:59], v[136:139], v[176:179], v[56:59]
	v_mfma_f32_16x16x32_bf16 v[44:47], v[128:131], v[192:195], v[44:47]
	v_mfma_f32_16x16x32_bf16 v[40:43], v[136:139], v[192:195], v[40:43]
	v_mfma_f32_16x16x32_bf16 v[28:31], v[128:131], v[200:203], v[28:31]
	v_mfma_f32_16x16x32_bf16 v[24:27], v[136:139], v[200:203], v[24:27]
	v_mfma_f32_16x16x32_bf16 v[12:15], v[128:131], v[208:211], v[12:15]
	v_mfma_f32_16x16x32_bf16 v[8:11], v[136:139], v[208:211], v[8:11]
	v_mfma_f32_16x16x32_bf16 v[60:63], v[132:135], v[180:183], v[60:63]
	v_mfma_f32_16x16x32_bf16 v[56:59], v[140:143], v[180:183], v[56:59]
	v_mfma_f32_16x16x32_bf16 v[44:47], v[132:135], v[196:199], v[44:47]
	v_mfma_f32_16x16x32_bf16 v[40:43], v[140:143], v[196:199], v[40:43]
	v_mfma_f32_16x16x32_bf16 v[28:31], v[132:135], v[204:207], v[28:31]
	v_mfma_f32_16x16x32_bf16 v[24:27], v[140:143], v[204:207], v[24:27]
	v_mfma_f32_16x16x32_bf16 v[12:15], v[132:135], v[212:215], v[12:15]
	v_mfma_f32_16x16x32_bf16 v[8:11], v[140:143], v[212:215], v[8:11]
	v_mfma_f32_16x16x32_bf16 v[52:55], v[144:147], v[176:179], v[52:55]
	v_mfma_f32_16x16x32_bf16 v[48:51], v[168:171], v[176:179], v[48:51]
	v_mfma_f32_16x16x32_bf16 v[36:39], v[144:147], v[192:195], v[36:39]
	v_mfma_f32_16x16x32_bf16 v[32:35], v[168:171], v[192:195], v[32:35]
	v_mfma_f32_16x16x32_bf16 v[20:23], v[144:147], v[200:203], v[20:23]
	v_mfma_f32_16x16x32_bf16 v[16:19], v[168:171], v[200:203], v[16:19]
	v_mfma_f32_16x16x32_bf16 v[4:7], v[144:147], v[208:211], v[4:7]
	v_mfma_f32_16x16x32_bf16 v[0:3], v[168:171], v[208:211], v[0:3]
	v_mfma_f32_16x16x32_bf16 v[52:55], v[148:151], v[180:183], v[52:55]
	v_mfma_f32_16x16x32_bf16 v[48:51], v[172:175], v[180:183], v[48:51]
	v_mfma_f32_16x16x32_bf16 v[36:39], v[148:151], v[196:199], v[36:39]
	v_mfma_f32_16x16x32_bf16 v[32:35], v[172:175], v[196:199], v[32:35]
	v_mfma_f32_16x16x32_bf16 v[20:23], v[148:151], v[204:207], v[20:23]
	v_mfma_f32_16x16x32_bf16 v[16:19], v[172:175], v[204:207], v[16:19]
	v_mfma_f32_16x16x32_bf16 v[4:7], v[148:151], v[212:215], v[4:7]
	v_mfma_f32_16x16x32_bf16 v[0:3], v[172:175], v[212:215], v[0:3]
	s_barrier
	s_add_i32 s59, 0, 0x18000
	s_add_i32 s60, 0, 0x1c000
	v_add_u32_e32 v140, s59, v187
	v_add_u32_e32 v172, s60, v187
	ds_read_b128 v[128:131], v140
	ds_read_b128 v[132:135], v140 offset:1024
	ds_read_b128 v[136:139], v140 offset:2048
	ds_read_b128 v[140:143], v140 offset:3072
	ds_read_b128 v[144:147], v172
	ds_read_b128 v[148:151], v172 offset:1024
	ds_read_b128 v[168:171], v172 offset:2048
	ds_read_b128 v[172:175], v172 offset:3072
	s_add_u32 s22, s30, 0x160000
	s_addc_u32 s23, s31, 0
	s_mov_b32 m0, s42
	v_lshl_add_u64 v[222:223], s[22:23], 0, v[152:153]
	ds_read_b128 v[176:179], v191 offset:32768
	ds_read_b128 v[180:183], v191 offset:33792
	ds_read_b128 v[192:195], v191 offset:34816
	ds_read_b128 v[196:199], v191 offset:35840
	ds_read_b128 v[200:203], v191 offset:36864
	ds_read_b128 v[204:207], v191 offset:37888
	ds_read_b128 v[208:211], v191 offset:38912
	ds_read_b128 v[212:215], v191 offset:39936
	global_load_lds_dwordx4 v[222:223], off
	v_lshl_add_u64 v[222:223], s[22:23], 0, v[156:157]
	s_mov_b32 m0, s43
	s_nop 0
	global_load_lds_dwordx4 v[222:223], off
	s_mov_b32 m0, s40
	s_nop 0
	global_load_lds_dwordx4 v[218:219], off
	s_mov_b32 m0, s41
	s_nop 0
	global_load_lds_dwordx4 v[220:221], off
	s_waitcnt vmcnt(10)
	s_waitcnt lgkmcnt(0)
	s_barrier
; #define PG8_STAGE(bufoff, gbase, voff) do { _Pragma("unroll") for (int _i = 0; _i < 2; ++_i) \
;         __builtin_amdgcn_global_load_lds((const unsigned*)((const char*)(gbase) + (voff)[_i]), (PG8_LAS unsigned*)(lds + (bufoff) + ldsw + _i * 8192), 16, 0, 0); } while (0)
; #define PG8_LDA(dst, b, h) do { _Pragma("unroll") for (int m = 0; m < 4; ++m) _Pragma("unroll") for (int k = 0; k < 2; ++k) dst[m][k] = *(const PG8_LAS bf16x8*)(lds + PG8_SA(b, h) + aoff + m * 2048 + k * 1024); } while (0)
; #define PG8_MMA(ai, bj, At, Bt) do { __builtin_amdgcn_s_setprio(1); _Pragma("unroll") for (int m = 0; m < 4; ++m) _Pragma("unroll") for (int n = 0; n < 2; ++n) _Pragma("unroll") for (int k = 0; k < 2; ++k) \
;         acc[ai][bj][m][n] = __builtin_amdgcn_mfma_f32_16x16x32_bf16(Bt[n][k], At[m][k], acc[ai][bj][m][n], 0, 0, 0); __builtin_amdgcn_s_setprio(0); } while (0)
; #define PG8_WAIT_V(n) asm volatile("s_waitcnt vmcnt(" #n ")" ::: "memory")
; #define PG8_WAIT_L(n) asm volatile("s_waitcnt lgkmcnt(" #n ")" ::: "memory")
; #define PG8_BAR __builtin_amdgcn_s_barrier()
; #define PG8_SCHED __builtin_amdgcn_sched_barrier(0)
; template <class Epi, class Sched, bool ALIGN_EPI = false, bool SP2 = false>
; __device__ __forceinline__ void gemm_phase(PG8_LAS unsigned char* lds, const Gemm g, const Sched& S, const Epi& E) {
;     ...
;             PG8_WAIT_V(8); PG8_WAIT_L(0); PG8_BAR; PG8_MMA(0, 0, At, B0); PG8_MMA(0, 1, At, B1); PG8_BAR; PG8_SCHED;
;             PG8_LDA(At, 1, 1); PG8_STAGE(PG8_SB(1, 0), b3, voffB); PG8_STAGE(PG8_SB(1, 1), b3 + hstep, voffB); PG8_STAGE(PG8_SA(1, 0), a3, voffA);
;             PG8_WAIT_V(8); PG8_WAIT_L(0); PG8_BAR; PG8_MMA(1, 0, At, B0); PG8_MMA(1, 1, At, B1); PG8_BAR; PG8_SCHED;
	s_waitcnt lgkmcnt(0)
	v_mfma_f32_16x16x32_bf16 v[124:127], v[128:131], v[176:179], v[124:127]
	v_mfma_f32_16x16x32_bf16 v[120:123], v[136:139], v[176:179], v[120:123]
	s_add_u32 s22, s28, 0x160080
	v_mfma_f32_16x16x32_bf16 v[108:111], v[128:131], v[192:195], v[108:111]
	v_mfma_f32_16x16x32_bf16 v[104:107], v[136:139], v[192:195], v[104:107]
	s_addc_u32 s23, s29, 0
	v_mfma_f32_16x16x32_bf16 v[92:95], v[128:131], v[200:203], v[92:95]
	v_mfma_f32_16x16x32_bf16 v[88:91], v[136:139], v[200:203], v[88:91]
	v_lshl_add_u64 v[184:185], v[184:185], 0, s[12:13]
	v_mfma_f32_16x16x32_bf16 v[76:79], v[128:131], v[208:211], v[76:79]
	v_mfma_f32_16x16x32_bf16 v[72:75], v[136:139], v[208:211], v[72:75]
	v_lshl_add_u64 v[216:217], v[216:217], 0, s[12:13]
	v_mfma_f32_16x16x32_bf16 v[124:127], v[132:135], v[180:183], v[124:127]
	v_mfma_f32_16x16x32_bf16 v[120:123], v[140:143], v[180:183], v[120:123]
	v_lshl_add_u64 v[246:247], s[22:23], 0, v[154:155]
	v_mfma_f32_16x16x32_bf16 v[108:111], v[132:135], v[196:199], v[108:111]
	v_mfma_f32_16x16x32_bf16 v[104:107], v[140:143], v[196:199], v[104:107]
	v_lshl_add_u64 v[248:249], s[22:23], 0, v[158:159]
	v_mfma_f32_16x16x32_bf16 v[92:95], v[132:135], v[204:207], v[92:95]
	v_mfma_f32_16x16x32_bf16 v[88:91], v[140:143], v[204:207], v[88:91]
	v_lshl_add_u64 v[250:251], v[218:219], 0, s[12:13]
	v_mfma_f32_16x16x32_bf16 v[76:79], v[132:135], v[212:215], v[76:79]
	v_mfma_f32_16x16x32_bf16 v[72:75], v[140:143], v[212:215], v[72:75]
	v_lshl_add_u64 v[252:253], v[220:221], 0, s[12:13]
	v_mfma_f32_16x16x32_bf16 v[116:119], v[144:147], v[176:179], v[116:119]
	v_mfma_f32_16x16x32_bf16 v[112:115], v[168:171], v[176:179], v[112:115]
	v_mfma_f32_16x16x32_bf16 v[100:103], v[144:147], v[192:195], v[100:103]
	v_mfma_f32_16x16x32_bf16 v[96:99], v[168:171], v[192:195], v[96:99]
	v_mfma_f32_16x16x32_bf16 v[84:87], v[144:147], v[200:203], v[84:87]
	v_mfma_f32_16x16x32_bf16 v[80:83], v[168:171], v[200:203], v[80:83]
	v_mfma_f32_16x16x32_bf16 v[68:71], v[144:147], v[208:211], v[68:71]
	v_mfma_f32_16x16x32_bf16 v[64:67], v[168:171], v[208:211], v[64:67]
	v_mfma_f32_16x16x32_bf16 v[116:119], v[148:151], v[180:183], v[116:119]
	v_mfma_f32_16x16x32_bf16 v[112:115], v[172:175], v[180:183], v[112:115]
	v_mfma_f32_16x16x32_bf16 v[100:103], v[148:151], v[196:199], v[100:103]
	v_mfma_f32_16x16x32_bf16 v[96:99], v[172:175], v[196:199], v[96:99]
	v_mfma_f32_16x16x32_bf16 v[84:87], v[148:151], v[204:207], v[84:87]
	v_mfma_f32_16x16x32_bf16 v[80:83], v[172:175], v[204:207], v[80:83]
	v_mfma_f32_16x16x32_bf16 v[68:71], v[148:151], v[212:215], v[68:71]
	v_mfma_f32_16x16x32_bf16 v[64:67], v[172:175], v[212:215], v[64:67]
	s_add_i32 s22, s59, s39
	s_mov_b32 m0, s22
	s_barrier
	global_load_lds_dwordx4 v[184:185], off
	s_add_i32 m0, s22, 0x2000
	s_add_i32 s28, s60, s39
	global_load_lds_dwordx4 v[216:217], off
	s_mov_b32 m0, s28
	s_nop 0
	global_load_lds_dwordx4 v[246:247], off
	s_add_i32 m0, s28, 0x2000
	s_nop 0
	global_load_lds_dwordx4 v[248:249], off
	ds_read_b128 v[176:179], v191 offset:49152
	ds_read_b128 v[180:183], v191 offset:50176
	ds_read_b128 v[192:195], v191 offset:51200
	ds_read_b128 v[196:199], v191 offset:52224
	ds_read_b128 v[200:203], v191 offset:53248
	ds_read_b128 v[204:207], v191 offset:54272
	ds_read_b128 v[208:211], v191 offset:55296
	ds_read_b128 v[212:215], v191 offset:56320
	s_waitcnt vmcnt(4)
	s_waitcnt lgkmcnt(0)
	s_barrier
	s_waitcnt lgkmcnt(0)
	v_mfma_f32_16x16x32_bf16 v[60:63], v[128:131], v[176:179], v[60:63]
	v_mfma_f32_16x16x32_bf16 v[56:59], v[136:139], v[176:179], v[56:59]
	v_mfma_f32_16x16x32_bf16 v[44:47], v[128:131], v[192:195], v[44:47]
	v_mfma_f32_16x16x32_bf16 v[40:43], v[136:139], v[192:195], v[40:43]
	v_mfma_f32_16x16x32_bf16 v[28:31], v[128:131], v[200:203], v[28:31]
	v_mfma_f32_16x16x32_bf16 v[24:27], v[136:139], v[200:203], v[24:27]
	v_mfma_f32_16x16x32_bf16 v[12:15], v[128:131], v[208:211], v[12:15]
	v_mfma_f32_16x16x32_bf16 v[8:11], v[136:139], v[208:211], v[8:11]
	v_mfma_f32_16x16x32_bf16 v[60:63], v[132:135], v[180:183], v[60:63]
	v_mfma_f32_16x16x32_bf16 v[56:59], v[140:143], v[180:183], v[56:59]
	v_mfma_f32_16x16x32_bf16 v[44:47], v[132:135], v[196:199], v[44:47]
	v_mfma_f32_16x16x32_bf16 v[40:43], v[140:143], v[196:199], v[40:43]
	v_mfma_f32_16x16x32_bf16 v[28:31], v[132:135], v[204:207], v[28:31]
	v_mfma_f32_16x16x32_bf16 v[24:27], v[140:143], v[204:207], v[24:27]
	v_mfma_f32_16x16x32_bf16 v[12:15], v[132:135], v[212:215], v[12:15]
	v_mfma_f32_16x16x32_bf16 v[8:11], v[140:143], v[212:215], v[8:11]
	v_mfma_f32_16x16x32_bf16 v[52:55], v[144:147], v[176:179], v[52:55]
	v_mfma_f32_16x16x32_bf16 v[48:51], v[168:171], v[176:179], v[48:51]
	v_mfma_f32_16x16x32_bf16 v[36:39], v[144:147], v[192:195], v[36:39]
	v_mfma_f32_16x16x32_bf16 v[32:35], v[168:171], v[192:195], v[32:35]
	s_add_i32 s58, s58, 2
	v_mfma_f32_16x16x32_bf16 v[20:23], v[144:147], v[200:203], v[20:23]
	v_mfma_f32_16x16x32_bf16 v[16:19], v[168:171], v[200:203], v[16:19]
	s_add_u32 s56, s56, 0x100
	v_mfma_f32_16x16x32_bf16 v[4:7], v[144:147], v[208:211], v[4:7]
	v_mfma_f32_16x16x32_bf16 v[0:3], v[168:171], v[208:211], v[0:3]
	s_addc_u32 s57, s57, 0
	v_mfma_f32_16x16x32_bf16 v[52:55], v[148:151], v[180:183], v[52:55]
	v_mfma_f32_16x16x32_bf16 v[48:51], v[172:175], v[180:183], v[48:51]
	v_mfma_f32_16x16x32_bf16 v[36:39], v[148:151], v[196:199], v[36:39]
	v_mfma_f32_16x16x32_bf16 v[32:35], v[172:175], v[196:199], v[32:35]
	v_mfma_f32_16x16x32_bf16 v[20:23], v[148:151], v[204:207], v[20:23]
	v_mfma_f32_16x16x32_bf16 v[16:19], v[172:175], v[204:207], v[16:19]
	v_mfma_f32_16x16x32_bf16 v[4:7], v[148:151], v[212:215], v[4:7]
	v_mfma_f32_16x16x32_bf16 v[0:3], v[172:175], v[212:215], v[0:3]
	s_barrier
	s_cmpk_gt_u32 s58, 0x55
	s_mov_b64 s[22:23], s[24:25]
	s_cbranch_scc0 .LBB0_788
	s_and_b64 vcc, exec, s[14:15]
	s_cbranch_vccz .LBB0_791
	s_barrier
